# GLA retention loop uses scaled state (2 packed ops per state update); GLA loops 64B-aligned
# speedup vs baseline: 1.0125x; 1.0125x over previous
.LBB0_242:
	s_andn2_b64 vcc, exec, s[8:9]
	s_cbranch_vccnz .LBB0_184
	s_lshr_b32 s20, s1, 2
	s_and_b32 s21, s1, 3
	s_lshr_b32 s14, s20, 4
	s_xor_b32 s14, s14, 1
	s_bfe_u32 s22, s20, 0x20002
	s_and_b32 s23, s20, 3
	s_mul_i32 s24, s14, 6144
	s_lshl_b32 s25, s23, 8
	s_add_u32 s24, s24, s25
	s_addk_i32 s24, 3072
	s_mul_i32 s25, s22, 0x6800000
	s_add_u32 s24, s24, s25
	s_add_u32 s8, s78, 0x15e00000
	s_addc_u32 s9, s79, 0
	s_add_u32 s8, s8, s24
	s_addc_u32 s9, s9, 0
	s_lshl_b32 s24, s14, 11
	s_lshl_b32 s25, s23, 8
	s_add_u32 s24, s24, s25
	s_lshl_b32 s25, s21, 6
	s_add_u32 s24, s24, s25
	s_addk_i32 s24, 1024
	s_lshl_b32 s25, s22, 25
	s_add_u32 s24, s24, s25
	s_add_u32 s10, s78, 0x2fe00000
	s_addc_u32 s11, s79, 0
	s_add_u32 s10, s10, s24
	s_addc_u32 s11, s11, 0
	s_lshl_b32 s24, s14, 23
	s_lshl_b32 s25, s22, 21
	s_add_u32 s24, s24, s25
	s_lshl_b32 s25, s23, 6
	s_add_u32 s24, s24, s25
	s_lshl_b32 s25, s21, 4
	s_add_u32 s24, s24, s25
	s_add_u32 s12, s78, 0x3ae90000
	s_addc_u32 s13, s79, 0
	s_add_u32 s12, s12, s24
	s_addc_u32 s13, s13, 0
	v_lshrrev_b32_e32 v154, 5, v163
	v_and_b32_e32 v155, 31, v163
	v_bfe_u32 v156, v163, 4, 4
	v_and_b32_e32 v157, 15, v163
	v_lshrrev_b32_e32 v160, 6, v163
	v_mul_u32_u24_e32 v130, 0x3400, v154
	v_lshl_add_u32 v130, v155, 3, v130
	v_mul_u32_u24_e32 v131, 0x3400, v156
	v_lshl_add_u32 v131, v157, 2, v131
	s_lshl_b32 s24, s21, 6
	s_addk_i32 s24, 2048
	v_add_u32_e32 v131, s24, v131
	v_readfirstlane_b32 s16, v160
	v_lshlrev_b32_e32 v132, 12, v154
	v_lshl_add_u32 v132, v155, 1, v132
	v_lshlrev_b32_e32 v133, 8, v154
	v_and_b32_e32 v134, 0xfffffff0, v163
	v_lshlrev_b32_e32 v135, 4, v157
	v_lshlrev_b32_e32 v139, 9, v154
	v_lshl_add_u32 v139, v155, 4, v139
	v_and_b32_e32 v158, 7, v157
	v_lshlrev_b32_e32 v158, 5, v158
	v_lshrrev_b32_e32 v159, 3, v157
	v_lshl_add_u32 v158, v159, 2, v158
	v_and_b32_e32 v159, 1, v156
	v_lshl_add_u32 v158, v159, 3, v158
	v_lshrrev_b32_e32 v159, 1, v156
	v_lshl_add_u32 v158, v159, 8, v158
	v_add_u32_e32 v140, 0x6000, v158
	v_add_u32_e32 v153, 0xe000, v158
	v_bfe_u32 v158, v163, 4, 1
	v_bfe_u32 v159, v163, 5, 1
	v_lshlrev_b32_e32 v158, 3, v158
	v_lshl_add_u32 v158, v159, 2, v158
	v_lshl_add_u32 v158, v158, 3, v160
	v_lshlrev_b32_e32 v158, 7, v158
	v_lshl_add_u32 v158, v157, 2, v158
	v_add_u32_e32 v141, 0x10000, v158
	v_add_u32_e32 v142, 0x10400, v158
	v_add_u32_e32 v143, 0x10800, v158
	v_add_u32_e32 v144, 0x10c00, v158
	v_add_u32_e32 v145, 0x14000, v158
	v_add_u32_e32 v146, 0x14400, v158
	v_add_u32_e32 v147, 0x14800, v158
	v_add_u32_e32 v148, 0x14c00, v158
	v_lshlrev_b32_e32 v161, 10, v154
	v_lshl_add_u32 v161, v155, 2, v161
	v_add_u32_e32 v149, 0x10000, v161
	v_add_u32_e32 v150, 0x14000, v161
	s_sub_u32 s24, 122, s23
	s_lshl_b32 s24, s24, 23
	v_mov_b32_e32 v100, s24
	v_sub_f32_e32 v100, 1.0, v100
	v_mov_b32_e32 v101, v100
	v_log_f32_e32 v158, v100
	v_add_u32_e32 v159, 1, v154
	v_cvt_f32_u32_e32 v159, v159
	v_mul_f32_e32 v159, v158, v159
	v_exp_f32_e32 v103, v159
	v_sub_f32_e32 v159, 0, v159
	v_mul_f32_e32 v158, 0x41800000, v158
	v_exp_f32_e32 v102, v159
	v_exp_f32_e32 v192, v158
	s_nop 0
	v_mov_b32_e32 v193, v192
	v_mov_b32_e32 v0, 0
	v_mov_b32_e32 v1, 0
	v_mov_b32_e32 v2, 0
	v_mov_b32_e32 v3, 0
	v_mov_b32_e32 v4, 0
	v_mov_b32_e32 v5, 0
	v_mov_b32_e32 v6, 0
	v_mov_b32_e32 v7, 0
	s_mov_b32 s18, 1
	s_mov_b32 s19, 1
	s_movk_i32 s15, 512
	global_load_dwordx2 v[120:121], v130, s[8:9]
	global_load_dwordx2 v[122:123], v130, s[8:9] offset:1024
	global_load_dword v124, v131, s[8:9]
	s_add_u32 s8, s8, 0x34000
	s_addc_u32 s9, s9, 0
	s_waitcnt vmcnt(0)
	v_lshlrev_b32_e32 v180, 16, v122
	v_and_b32_e32 v181, s69, v122
	v_lshlrev_b32_e32 v182, 16, v123
	v_and_b32_e32 v183, s69, v123
	s_cmp_eq_u32 s14, 0
	s_cbranch_scc1 .Lgla_st_join_1
	v_mul_f32_e32 v180, 0x3fb8aa3b, v180
	v_mul_f32_e32 v181, 0x3fb8aa3b, v181
	v_mul_f32_e32 v182, 0x3fb8aa3b, v182
	v_mul_f32_e32 v183, 0x3fb8aa3b, v183
	v_exp_f32_e32 v180, v180
	v_exp_f32_e32 v181, v181
	v_exp_f32_e32 v182, v182
	v_exp_f32_e32 v183, v183
.Lgla_st_join_1:
	v_lshlrev_b32_e32 v184, 16, v120
	v_and_b32_e32 v185, s69, v120
	v_lshlrev_b32_e32 v186, 16, v121
	v_and_b32_e32 v187, s69, v121
	v_lshlrev_b32_e32 v188, 16, v124
	v_and_b32_e32 v189, s69, v124
	s_cmp_eq_u32 s14, 0
	s_cbranch_scc0 .Lgla_st_nosc_1
	v_pk_mul_f32 v[180:181], v[180:181], v[102:103] op_sel_hi:[1,0]
	v_pk_mul_f32 v[182:183], v[182:183], v[102:103] op_sel_hi:[1,0]
	v_pk_mul_f32 v[184:185], v[184:185], v[102:103] op_sel:[0,1] op_sel_hi:[1,1]
	v_pk_mul_f32 v[186:187], v[186:187], v[102:103] op_sel:[0,1] op_sel_hi:[1,1]
.Lgla_st_nosc_1:
	ds_write_b128 v139, v[180:183] offset:8192
	ds_write_b128 v139, v[184:187] offset:16384
	ds_write2_b32 v140, v188, v189 offset1:4
	global_load_dwordx2 v[126:127], v130, s[8:9]
	global_load_dwordx2 v[190:191], v130, s[8:9] offset:1024
	global_load_dword v119, v131, s[8:9]
	s_add_u32 s8, s8, 0x34000
	s_addc_u32 s9, s9, 0
	global_load_dword v152, v131, s[8:9]
	global_load_dword v152, v131, s[8:9]
	global_load_dwordx2 v[120:121], v130, s[8:9]
	global_load_dwordx2 v[122:123], v130, s[8:9] offset:1024
	global_load_dword v124, v131, s[8:9]
	s_add_u32 s8, s8, 0x34000
	s_addc_u32 s9, s9, 0
	global_load_dword v152, v131, s[8:9]
	global_load_dword v152, v131, s[8:9]
	s_waitcnt lgkmcnt(0)
	s_barrier
	s_cmp_eq_u32 s14, 0
	s_cbranch_scc1 .Lgla_loop_ret
	.p2align 6

.Lgla_st_join_2:
	v_lshlrev_b32_e32 v184, 16, v126
	v_and_b32_e32 v185, s69, v126
	v_lshlrev_b32_e32 v186, 16, v127
	v_and_b32_e32 v187, s69, v127
	v_lshlrev_b32_e32 v188, 16, v119
	v_and_b32_e32 v189, s69, v119
	s_cmp_eq_u32 s14, 0
	s_cbranch_scc0 .Lgla_st_nosc_2
	v_pk_mul_f32 v[180:181], v[180:181], v[102:103] op_sel_hi:[1,0]
	v_pk_mul_f32 v[182:183], v[182:183], v[102:103] op_sel_hi:[1,0]
	v_pk_mul_f32 v[184:185], v[184:185], v[102:103] op_sel:[0,1] op_sel_hi:[1,1]
	v_pk_mul_f32 v[186:187], v[186:187], v[102:103] op_sel:[0,1] op_sel_hi:[1,1]
.Lgla_st_nosc_2:
	ds_write_b128 v139, v[180:183] offset:40960
	ds_write_b128 v139, v[184:187] offset:49152
	ds_write2_b32 v153, v188, v189 offset1:4
	global_load_dwordx2 v[126:127], v130, s[8:9]
	global_load_dwordx2 v[190:191], v130, s[8:9] offset:1024
	global_load_dword v119, v131, s[8:9]
	s_add_u32 s8, s8, 0x34000
	s_addc_u32 s9, s9, 0
	s_waitcnt lgkmcnt(3)
	v_add_f32_e32 v112, v104, v105
	v_add_f32_e32 v112, v112, v106
	v_add_f32_e32 v112, v112, v107
	v_add_f32_e32 v112, v112, v108
	v_add_f32_e32 v112, v112, v109
	v_add_f32_e32 v112, v112, v110
	v_add_f32_e32 v112, v112, v111
	v_mul_f32_e32 v113, v112, v112
	v_cvt_pk_bf16_f32 v116, v112, v129
	v_mov_b32_e32 v117, v112
	v_mov_b32_e32 v118, v113
	global_store_short v132, v116, s[10:11]
	s_nop 1
	v_permlane16_swap_b32_e32 v112, v117
	v_permlane16_swap_b32_e32 v113, v118
	v_add_f32_e32 v112, v112, v117
	v_add_f32_e32 v113, v113, v118
	s_nop 1
	v_add_f32_dpp v112, v112, v112 row_ror:8 row_mask:0xf bank_mask:0xf
	v_add_f32_dpp v113, v113, v113 row_ror:8 row_mask:0xf bank_mask:0xf
	s_nop 1
	v_add_f32_dpp v112, v112, v112 row_ror:4 row_mask:0xf bank_mask:0xf
	v_add_f32_dpp v113, v113, v113 row_ror:4 row_mask:0xf bank_mask:0xf
	s_nop 1
	v_add_f32_dpp v112, v112, v112 row_ror:2 row_mask:0xf bank_mask:0xf
	v_add_f32_dpp v113, v113, v113 row_ror:2 row_mask:0xf bank_mask:0xf
	s_nop 1
	v_add_f32_dpp v112, v112, v112 row_ror:1 row_mask:0xf bank_mask:0xf
	v_add_f32_dpp v113, v113, v113 row_ror:1 row_mask:0xf bank_mask:0xf
	v_mov_b32_e32 v114, 0
	v_mov_b32_e32 v115, 0
	s_mov_b64 exec, s[18:19]
	global_store_dwordx4 v133, v[112:115], s[12:13]
	s_mov_b64 exec, -1
	s_cmp_eq_u32 s15, 512
	s_cselect_b32 s20, 0, 0x10000
	s_cselect_b32 s21, 0, 0x1000
	s_add_u32 s10, s10, s20
	s_addc_u32 s11, s11, 0
	s_add_u32 s12, s12, s21
	s_addc_u32 s13, s13, 0
	ds_read_b128 v[80:83], v135 offset:24576
	ds_read_b128 v[40:43], v134 offset:8192
	ds_read_b128 v[44:47], v134 offset:16384
	ds_read_b128 v[48:51], v134 offset:8704
	ds_read_b128 v[52:55], v134 offset:16896
	ds_read_b128 v[84:87], v135 offset:24832
	ds_read_b128 v[56:59], v134 offset:9216
	ds_read_b128 v[60:63], v134 offset:17408
	ds_read_b128 v[64:67], v134 offset:9728
	ds_read_b128 v[68:71], v134 offset:17920
	s_waitcnt lgkmcnt(7)
	v_pk_add_f32 v[92:93], v[0:1], v[80:81] neg_lo:[0,1] neg_hi:[0,1]
	v_pk_add_f32 v[94:95], v[2:3], v[80:81] neg_lo:[0,1] neg_hi:[0,1]
	v_pk_add_f32 v[96:97], v[4:5], v[80:81] neg_lo:[0,1] neg_hi:[0,1]
	v_pk_add_f32 v[98:99], v[6:7], v[80:81] neg_lo:[0,1] neg_hi:[0,1]
	v_pk_fma_f32 v[0:1], v[92:93], v[40:41], v[80:81] op_sel_hi:[1,0,1]
	v_pk_fma_f32 v[2:3], v[94:95], v[40:41], v[80:81] op_sel:[0,1,0] op_sel_hi:[1,1,1]
	v_pk_fma_f32 v[4:5], v[96:97], v[42:43], v[80:81] op_sel_hi:[1,0,1]
	v_pk_fma_f32 v[6:7], v[98:99], v[42:43], v[80:81] op_sel:[0,1,0] op_sel_hi:[1,1,1]
	ds_read_b128 v[88:91], v135 offset:25088
	ds_read_b128 v[72:75], v134 offset:10240
	ds_read_b128 v[76:79], v134 offset:18432
	s_waitcnt lgkmcnt(8)
	v_pk_add_f32 v[92:93], v[0:1], v[82:83] neg_lo:[0,1] neg_hi:[0,1]
	v_pk_mul_f32 v[8:9], v[0:1], v[44:45] op_sel_hi:[1,0]
	v_pk_add_f32 v[94:95], v[2:3], v[82:83] neg_lo:[0,1] neg_hi:[0,1]
	v_pk_fma_f32 v[8:9], v[2:3], v[44:45], v[8:9] op_sel:[0,1,0] op_sel_hi:[1,1,1]
	v_pk_add_f32 v[96:97], v[4:5], v[82:83] neg_lo:[0,1] neg_hi:[0,1]
	v_pk_fma_f32 v[8:9], v[4:5], v[46:47], v[8:9] op_sel_hi:[1,0,1]
	v_pk_add_f32 v[98:99], v[6:7], v[82:83] neg_lo:[0,1] neg_hi:[0,1]
	v_pk_fma_f32 v[8:9], v[6:7], v[46:47], v[8:9] op_sel:[0,1,0] op_sel_hi:[1,1,1]
	v_pk_fma_f32 v[0:1], v[92:93], v[48:49], v[82:83] op_sel_hi:[1,0,1]
	v_pk_fma_f32 v[2:3], v[94:95], v[48:49], v[82:83] op_sel:[0,1,0] op_sel_hi:[1,1,1]
	v_pk_fma_f32 v[4:5], v[96:97], v[50:51], v[82:83] op_sel_hi:[1,0,1]
	v_pk_fma_f32 v[6:7], v[98:99], v[50:51], v[82:83] op_sel:[0,1,0] op_sel_hi:[1,1,1]
	ds_read_b128 v[40:43], v134 offset:10752
	ds_read_b128 v[44:47], v134 offset:18944
	s_waitcnt lgkmcnt(7)
	v_pk_add_f32 v[92:93], v[0:1], v[84:85] neg_lo:[0,1] neg_hi:[0,1]
	v_pk_mul_f32 v[10:11], v[0:1], v[52:53] op_sel_hi:[1,0]
	v_pk_add_f32 v[94:95], v[2:3], v[84:85] neg_lo:[0,1] neg_hi:[0,1]
	v_pk_fma_f32 v[10:11], v[2:3], v[52:53], v[10:11] op_sel:[0,1,0] op_sel_hi:[1,1,1]
	v_pk_add_f32 v[96:97], v[4:5], v[84:85] neg_lo:[0,1] neg_hi:[0,1]
	v_pk_fma_f32 v[10:11], v[4:5], v[54:55], v[10:11] op_sel_hi:[1,0,1]
	v_pk_add_f32 v[98:99], v[6:7], v[84:85] neg_lo:[0,1] neg_hi:[0,1]
	v_pk_fma_f32 v[10:11], v[6:7], v[54:55], v[10:11] op_sel:[0,1,0] op_sel_hi:[1,1,1]
	v_pk_fma_f32 v[0:1], v[92:93], v[56:57], v[84:85] op_sel_hi:[1,0,1]
	v_pk_fma_f32 v[2:3], v[94:95], v[56:57], v[84:85] op_sel:[0,1,0] op_sel_hi:[1,1,1]
	v_pk_fma_f32 v[4:5], v[96:97], v[58:59], v[84:85] op_sel_hi:[1,0,1]
	v_pk_fma_f32 v[6:7], v[98:99], v[58:59], v[84:85] op_sel:[0,1,0] op_sel_hi:[1,1,1]
	ds_read_b128 v[80:83], v135 offset:25344
	ds_read_b128 v[48:51], v134 offset:11264
	ds_read_b128 v[52:55], v134 offset:19456
	s_waitcnt lgkmcnt(8)
	v_pk_add_f32 v[92:93], v[0:1], v[86:87] neg_lo:[0,1] neg_hi:[0,1]
	v_pk_mul_f32 v[12:13], v[0:1], v[60:61] op_sel_hi:[1,0]
	v_pk_add_f32 v[94:95], v[2:3], v[86:87] neg_lo:[0,1] neg_hi:[0,1]
	v_pk_fma_f32 v[12:13], v[2:3], v[60:61], v[12:13] op_sel:[0,1,0] op_sel_hi:[1,1,1]
	v_pk_add_f32 v[96:97], v[4:5], v[86:87] neg_lo:[0,1] neg_hi:[0,1]
	v_pk_fma_f32 v[12:13], v[4:5], v[62:63], v[12:13] op_sel_hi:[1,0,1]
	v_pk_add_f32 v[98:99], v[6:7], v[86:87] neg_lo:[0,1] neg_hi:[0,1]
	v_pk_fma_f32 v[12:13], v[6:7], v[62:63], v[12:13] op_sel:[0,1,0] op_sel_hi:[1,1,1]
	v_pk_fma_f32 v[0:1], v[92:93], v[64:65], v[86:87] op_sel_hi:[1,0,1]
	v_pk_fma_f32 v[2:3], v[94:95], v[64:65], v[86:87] op_sel:[0,1,0] op_sel_hi:[1,1,1]
	v_pk_fma_f32 v[4:5], v[96:97], v[66:67], v[86:87] op_sel_hi:[1,0,1]
	v_pk_fma_f32 v[6:7], v[98:99], v[66:67], v[86:87] op_sel:[0,1,0] op_sel_hi:[1,1,1]
	ds_read_b128 v[56:59], v134 offset:11776
	ds_read_b128 v[60:63], v134 offset:19968
	s_waitcnt lgkmcnt(7)
	v_pk_add_f32 v[92:93], v[0:1], v[88:89] neg_lo:[0,1] neg_hi:[0,1]
	v_pk_mul_f32 v[14:15], v[0:1], v[68:69] op_sel_hi:[1,0]
	v_pk_add_f32 v[94:95], v[2:3], v[88:89] neg_lo:[0,1] neg_hi:[0,1]
	v_pk_fma_f32 v[14:15], v[2:3], v[68:69], v[14:15] op_sel:[0,1,0] op_sel_hi:[1,1,1]
	v_pk_add_f32 v[96:97], v[4:5], v[88:89] neg_lo:[0,1] neg_hi:[0,1]
	v_pk_fma_f32 v[14:15], v[4:5], v[70:71], v[14:15] op_sel_hi:[1,0,1]
	v_pk_add_f32 v[98:99], v[6:7], v[88:89] neg_lo:[0,1] neg_hi:[0,1]
	v_pk_fma_f32 v[14:15], v[6:7], v[70:71], v[14:15] op_sel:[0,1,0] op_sel_hi:[1,1,1]
	v_pk_fma_f32 v[0:1], v[92:93], v[72:73], v[88:89] op_sel_hi:[1,0,1]
	v_pk_fma_f32 v[2:3], v[94:95], v[72:73], v[88:89] op_sel:[0,1,0] op_sel_hi:[1,1,1]
	v_pk_fma_f32 v[4:5], v[96:97], v[74:75], v[88:89] op_sel_hi:[1,0,1]
	v_pk_fma_f32 v[6:7], v[98:99], v[74:75], v[88:89] op_sel:[0,1,0] op_sel_hi:[1,1,1]
	ds_read_b128 v[84:87], v135 offset:25600
	ds_read_b128 v[64:67], v134 offset:12288
	ds_read_b128 v[68:71], v134 offset:20480
	s_waitcnt lgkmcnt(8)
	v_pk_add_f32 v[92:93], v[0:1], v[90:91] neg_lo:[0,1] neg_hi:[0,1]
	v_pk_mul_f32 v[16:17], v[0:1], v[76:77] op_sel_hi:[1,0]
	v_pk_add_f32 v[94:95], v[2:3], v[90:91] neg_lo:[0,1] neg_hi:[0,1]
	v_pk_fma_f32 v[16:17], v[2:3], v[76:77], v[16:17] op_sel:[0,1,0] op_sel_hi:[1,1,1]
	v_pk_add_f32 v[96:97], v[4:5], v[90:91] neg_lo:[0,1] neg_hi:[0,1]
	v_pk_fma_f32 v[16:17], v[4:5], v[78:79], v[16:17] op_sel_hi:[1,0,1]
	v_pk_add_f32 v[98:99], v[6:7], v[90:91] neg_lo:[0,1] neg_hi:[0,1]
	v_pk_fma_f32 v[16:17], v[6:7], v[78:79], v[16:17] op_sel:[0,1,0] op_sel_hi:[1,1,1]
	v_pk_fma_f32 v[0:1], v[92:93], v[40:41], v[90:91] op_sel_hi:[1,0,1]
	v_pk_fma_f32 v[2:3], v[94:95], v[40:41], v[90:91] op_sel:[0,1,0] op_sel_hi:[1,1,1]
	v_pk_fma_f32 v[4:5], v[96:97], v[42:43], v[90:91] op_sel_hi:[1,0,1]
	v_pk_fma_f32 v[6:7], v[98:99], v[42:43], v[90:91] op_sel:[0,1,0] op_sel_hi:[1,1,1]
	ds_read_b128 v[72:75], v134 offset:12800
	ds_read_b128 v[76:79], v134 offset:20992
	s_waitcnt lgkmcnt(7)
	v_pk_add_f32 v[92:93], v[0:1], v[80:81] neg_lo:[0,1] neg_hi:[0,1]
	v_pk_mul_f32 v[18:19], v[0:1], v[44:45] op_sel_hi:[1,0]
	v_pk_add_f32 v[94:95], v[2:3], v[80:81] neg_lo:[0,1] neg_hi:[0,1]
	v_pk_fma_f32 v[18:19], v[2:3], v[44:45], v[18:19] op_sel:[0,1,0] op_sel_hi:[1,1,1]
	v_pk_add_f32 v[96:97], v[4:5], v[80:81] neg_lo:[0,1] neg_hi:[0,1]
	v_pk_fma_f32 v[18:19], v[4:5], v[46:47], v[18:19] op_sel_hi:[1,0,1]
	v_pk_add_f32 v[98:99], v[6:7], v[80:81] neg_lo:[0,1] neg_hi:[0,1]
	v_pk_fma_f32 v[18:19], v[6:7], v[46:47], v[18:19] op_sel:[0,1,0] op_sel_hi:[1,1,1]
	v_pk_fma_f32 v[0:1], v[92:93], v[48:49], v[80:81] op_sel_hi:[1,0,1]
	v_pk_fma_f32 v[2:3], v[94:95], v[48:49], v[80:81] op_sel:[0,1,0] op_sel_hi:[1,1,1]
	v_pk_fma_f32 v[4:5], v[96:97], v[50:51], v[80:81] op_sel_hi:[1,0,1]
	v_pk_fma_f32 v[6:7], v[98:99], v[50:51], v[80:81] op_sel:[0,1,0] op_sel_hi:[1,1,1]
	ds_read_b128 v[88:91], v135 offset:25856
	ds_read_b128 v[40:43], v134 offset:13312
	ds_read_b128 v[44:47], v134 offset:21504
	s_waitcnt lgkmcnt(8)
	v_pk_add_f32 v[92:93], v[0:1], v[82:83] neg_lo:[0,1] neg_hi:[0,1]
	v_pk_mul_f32 v[20:21], v[0:1], v[52:53] op_sel_hi:[1,0]
	v_pk_add_f32 v[94:95], v[2:3], v[82:83] neg_lo:[0,1] neg_hi:[0,1]
	v_pk_fma_f32 v[20:21], v[2:3], v[52:53], v[20:21] op_sel:[0,1,0] op_sel_hi:[1,1,1]
	v_pk_add_f32 v[96:97], v[4:5], v[82:83] neg_lo:[0,1] neg_hi:[0,1]
	v_pk_fma_f32 v[20:21], v[4:5], v[54:55], v[20:21] op_sel_hi:[1,0,1]
	v_pk_add_f32 v[98:99], v[6:7], v[82:83] neg_lo:[0,1] neg_hi:[0,1]
	v_pk_fma_f32 v[20:21], v[6:7], v[54:55], v[20:21] op_sel:[0,1,0] op_sel_hi:[1,1,1]
	v_pk_fma_f32 v[0:1], v[92:93], v[56:57], v[82:83] op_sel_hi:[1,0,1]
	v_pk_fma_f32 v[2:3], v[94:95], v[56:57], v[82:83] op_sel:[0,1,0] op_sel_hi:[1,1,1]
	v_pk_fma_f32 v[4:5], v[96:97], v[58:59], v[82:83] op_sel_hi:[1,0,1]
	v_pk_fma_f32 v[6:7], v[98:99], v[58:59], v[82:83] op_sel:[0,1,0] op_sel_hi:[1,1,1]
	ds_read_b128 v[48:51], v134 offset:13824
	ds_read_b128 v[52:55], v134 offset:22016
	s_waitcnt lgkmcnt(7)
	v_pk_add_f32 v[92:93], v[0:1], v[84:85] neg_lo:[0,1] neg_hi:[0,1]
	v_pk_mul_f32 v[22:23], v[0:1], v[60:61] op_sel_hi:[1,0]
	v_pk_add_f32 v[94:95], v[2:3], v[84:85] neg_lo:[0,1] neg_hi:[0,1]
	v_pk_fma_f32 v[22:23], v[2:3], v[60:61], v[22:23] op_sel:[0,1,0] op_sel_hi:[1,1,1]
	v_pk_add_f32 v[96:97], v[4:5], v[84:85] neg_lo:[0,1] neg_hi:[0,1]
	v_pk_fma_f32 v[22:23], v[4:5], v[62:63], v[22:23] op_sel_hi:[1,0,1]
	v_pk_add_f32 v[98:99], v[6:7], v[84:85] neg_lo:[0,1] neg_hi:[0,1]
	v_pk_fma_f32 v[22:23], v[6:7], v[62:63], v[22:23] op_sel:[0,1,0] op_sel_hi:[1,1,1]
	v_pk_fma_f32 v[0:1], v[92:93], v[64:65], v[84:85] op_sel_hi:[1,0,1]
	v_pk_fma_f32 v[2:3], v[94:95], v[64:65], v[84:85] op_sel:[0,1,0] op_sel_hi:[1,1,1]
	v_pk_fma_f32 v[4:5], v[96:97], v[66:67], v[84:85] op_sel_hi:[1,0,1]
	v_pk_fma_f32 v[6:7], v[98:99], v[66:67], v[84:85] op_sel:[0,1,0] op_sel_hi:[1,1,1]
	ds_read_b128 v[80:83], v135 offset:26112
	ds_read_b128 v[56:59], v134 offset:14336
	ds_read_b128 v[60:63], v134 offset:22528
	s_waitcnt lgkmcnt(8)
	v_pk_add_f32 v[92:93], v[0:1], v[86:87] neg_lo:[0,1] neg_hi:[0,1]
	v_pk_mul_f32 v[24:25], v[0:1], v[68:69] op_sel_hi:[1,0]
	v_pk_add_f32 v[94:95], v[2:3], v[86:87] neg_lo:[0,1] neg_hi:[0,1]
	v_pk_fma_f32 v[24:25], v[2:3], v[68:69], v[24:25] op_sel:[0,1,0] op_sel_hi:[1,1,1]
	v_pk_add_f32 v[96:97], v[4:5], v[86:87] neg_lo:[0,1] neg_hi:[0,1]
	v_pk_fma_f32 v[24:25], v[4:5], v[70:71], v[24:25] op_sel_hi:[1,0,1]
	v_pk_add_f32 v[98:99], v[6:7], v[86:87] neg_lo:[0,1] neg_hi:[0,1]
	v_pk_fma_f32 v[24:25], v[6:7], v[70:71], v[24:25] op_sel:[0,1,0] op_sel_hi:[1,1,1]
	v_pk_fma_f32 v[0:1], v[92:93], v[72:73], v[86:87] op_sel_hi:[1,0,1]
	v_pk_fma_f32 v[2:3], v[94:95], v[72:73], v[86:87] op_sel:[0,1,0] op_sel_hi:[1,1,1]
	v_pk_fma_f32 v[4:5], v[96:97], v[74:75], v[86:87] op_sel_hi:[1,0,1]
	v_pk_fma_f32 v[6:7], v[98:99], v[74:75], v[86:87] op_sel:[0,1,0] op_sel_hi:[1,1,1]
	ds_read_b128 v[64:67], v134 offset:14848
	ds_read_b128 v[68:71], v134 offset:23040
	s_waitcnt lgkmcnt(7)
	v_pk_add_f32 v[92:93], v[0:1], v[88:89] neg_lo:[0,1] neg_hi:[0,1]
	v_pk_mul_f32 v[26:27], v[0:1], v[76:77] op_sel_hi:[1,0]
	v_pk_add_f32 v[94:95], v[2:3], v[88:89] neg_lo:[0,1] neg_hi:[0,1]
	v_pk_fma_f32 v[26:27], v[2:3], v[76:77], v[26:27] op_sel:[0,1,0] op_sel_hi:[1,1,1]
	v_pk_add_f32 v[96:97], v[4:5], v[88:89] neg_lo:[0,1] neg_hi:[0,1]
	v_pk_fma_f32 v[26:27], v[4:5], v[78:79], v[26:27] op_sel_hi:[1,0,1]
	v_pk_add_f32 v[98:99], v[6:7], v[88:89] neg_lo:[0,1] neg_hi:[0,1]
	v_pk_fma_f32 v[26:27], v[6:7], v[78:79], v[26:27] op_sel:[0,1,0] op_sel_hi:[1,1,1]
	v_pk_fma_f32 v[0:1], v[92:93], v[40:41], v[88:89] op_sel_hi:[1,0,1]
	v_pk_fma_f32 v[2:3], v[94:95], v[40:41], v[88:89] op_sel:[0,1,0] op_sel_hi:[1,1,1]
	v_pk_fma_f32 v[4:5], v[96:97], v[42:43], v[88:89] op_sel_hi:[1,0,1]
	v_pk_fma_f32 v[6:7], v[98:99], v[42:43], v[88:89] op_sel:[0,1,0] op_sel_hi:[1,1,1]
	ds_read_b128 v[84:87], v135 offset:26368
	ds_read_b128 v[72:75], v134 offset:15360
	ds_read_b128 v[76:79], v134 offset:23552
	s_waitcnt lgkmcnt(8)
	v_pk_add_f32 v[92:93], v[0:1], v[90:91] neg_lo:[0,1] neg_hi:[0,1]
	v_pk_mul_f32 v[28:29], v[0:1], v[44:45] op_sel_hi:[1,0]
	v_pk_add_f32 v[94:95], v[2:3], v[90:91] neg_lo:[0,1] neg_hi:[0,1]
	v_pk_fma_f32 v[28:29], v[2:3], v[44:45], v[28:29] op_sel:[0,1,0] op_sel_hi:[1,1,1]
	v_pk_add_f32 v[96:97], v[4:5], v[90:91] neg_lo:[0,1] neg_hi:[0,1]
	v_pk_fma_f32 v[28:29], v[4:5], v[46:47], v[28:29] op_sel_hi:[1,0,1]
	v_pk_add_f32 v[98:99], v[6:7], v[90:91] neg_lo:[0,1] neg_hi:[0,1]
	v_pk_fma_f32 v[28:29], v[6:7], v[46:47], v[28:29] op_sel:[0,1,0] op_sel_hi:[1,1,1]
	v_pk_fma_f32 v[0:1], v[92:93], v[48:49], v[90:91] op_sel_hi:[1,0,1]
	v_pk_fma_f32 v[2:3], v[94:95], v[48:49], v[90:91] op_sel:[0,1,0] op_sel_hi:[1,1,1]
	v_pk_fma_f32 v[4:5], v[96:97], v[50:51], v[90:91] op_sel_hi:[1,0,1]
	v_pk_fma_f32 v[6:7], v[98:99], v[50:51], v[90:91] op_sel:[0,1,0] op_sel_hi:[1,1,1]
	ds_read_b128 v[40:43], v134 offset:15872
	ds_read_b128 v[44:47], v134 offset:24064
	s_waitcnt lgkmcnt(7)
	v_pk_add_f32 v[92:93], v[0:1], v[80:81] neg_lo:[0,1] neg_hi:[0,1]
	v_pk_mul_f32 v[30:31], v[0:1], v[52:53] op_sel_hi:[1,0]
	v_pk_add_f32 v[94:95], v[2:3], v[80:81] neg_lo:[0,1] neg_hi:[0,1]
	v_pk_fma_f32 v[30:31], v[2:3], v[52:53], v[30:31] op_sel:[0,1,0] op_sel_hi:[1,1,1]
	v_pk_add_f32 v[96:97], v[4:5], v[80:81] neg_lo:[0,1] neg_hi:[0,1]
	v_pk_fma_f32 v[30:31], v[4:5], v[54:55], v[30:31] op_sel_hi:[1,0,1]
	v_pk_add_f32 v[98:99], v[6:7], v[80:81] neg_lo:[0,1] neg_hi:[0,1]
	v_pk_fma_f32 v[30:31], v[6:7], v[54:55], v[30:31] op_sel:[0,1,0] op_sel_hi:[1,1,1]
	v_pk_fma_f32 v[0:1], v[92:93], v[56:57], v[80:81] op_sel_hi:[1,0,1]
	v_pk_fma_f32 v[2:3], v[94:95], v[56:57], v[80:81] op_sel:[0,1,0] op_sel_hi:[1,1,1]
	v_pk_fma_f32 v[4:5], v[96:97], v[58:59], v[80:81] op_sel_hi:[1,0,1]
	v_pk_fma_f32 v[6:7], v[98:99], v[58:59], v[80:81] op_sel:[0,1,0] op_sel_hi:[1,1,1]
	s_waitcnt lgkmcnt(5)
	v_pk_add_f32 v[92:93], v[0:1], v[82:83] neg_lo:[0,1] neg_hi:[0,1]
	v_pk_mul_f32 v[32:33], v[0:1], v[60:61] op_sel_hi:[1,0]
	v_pk_add_f32 v[94:95], v[2:3], v[82:83] neg_lo:[0,1] neg_hi:[0,1]
	v_pk_fma_f32 v[32:33], v[2:3], v[60:61], v[32:33] op_sel:[0,1,0] op_sel_hi:[1,1,1]
	v_pk_add_f32 v[96:97], v[4:5], v[82:83] neg_lo:[0,1] neg_hi:[0,1]
	v_pk_fma_f32 v[32:33], v[4:5], v[62:63], v[32:33] op_sel_hi:[1,0,1]
	v_pk_add_f32 v[98:99], v[6:7], v[82:83] neg_lo:[0,1] neg_hi:[0,1]
	v_pk_fma_f32 v[32:33], v[6:7], v[62:63], v[32:33] op_sel:[0,1,0] op_sel_hi:[1,1,1]
	v_pk_fma_f32 v[0:1], v[92:93], v[64:65], v[82:83] op_sel_hi:[1,0,1]
	v_pk_fma_f32 v[2:3], v[94:95], v[64:65], v[82:83] op_sel:[0,1,0] op_sel_hi:[1,1,1]
	v_pk_fma_f32 v[4:5], v[96:97], v[66:67], v[82:83] op_sel_hi:[1,0,1]
	v_pk_fma_f32 v[6:7], v[98:99], v[66:67], v[82:83] op_sel:[0,1,0] op_sel_hi:[1,1,1]
	s_waitcnt lgkmcnt(2)
	v_pk_add_f32 v[92:93], v[0:1], v[84:85] neg_lo:[0,1] neg_hi:[0,1]
	v_pk_mul_f32 v[34:35], v[0:1], v[68:69] op_sel_hi:[1,0]
	v_pk_add_f32 v[94:95], v[2:3], v[84:85] neg_lo:[0,1] neg_hi:[0,1]
	v_pk_fma_f32 v[34:35], v[2:3], v[68:69], v[34:35] op_sel:[0,1,0] op_sel_hi:[1,1,1]
	v_pk_add_f32 v[96:97], v[4:5], v[84:85] neg_lo:[0,1] neg_hi:[0,1]
	v_pk_fma_f32 v[34:35], v[4:5], v[70:71], v[34:35] op_sel_hi:[1,0,1]
	v_pk_add_f32 v[98:99], v[6:7], v[84:85] neg_lo:[0,1] neg_hi:[0,1]
	v_pk_fma_f32 v[34:35], v[6:7], v[70:71], v[34:35] op_sel:[0,1,0] op_sel_hi:[1,1,1]
	v_pk_fma_f32 v[0:1], v[92:93], v[72:73], v[84:85] op_sel_hi:[1,0,1]
	v_pk_fma_f32 v[2:3], v[94:95], v[72:73], v[84:85] op_sel:[0,1,0] op_sel_hi:[1,1,1]
	v_pk_fma_f32 v[4:5], v[96:97], v[74:75], v[84:85] op_sel_hi:[1,0,1]
	v_pk_fma_f32 v[6:7], v[98:99], v[74:75], v[84:85] op_sel:[0,1,0] op_sel_hi:[1,1,1]
	s_waitcnt lgkmcnt(0)
	v_pk_add_f32 v[92:93], v[0:1], v[86:87] neg_lo:[0,1] neg_hi:[0,1]
	v_pk_mul_f32 v[36:37], v[0:1], v[76:77] op_sel_hi:[1,0]
	v_pk_add_f32 v[94:95], v[2:3], v[86:87] neg_lo:[0,1] neg_hi:[0,1]
	v_pk_fma_f32 v[36:37], v[2:3], v[76:77], v[36:37] op_sel:[0,1,0] op_sel_hi:[1,1,1]
	v_pk_add_f32 v[96:97], v[4:5], v[86:87] neg_lo:[0,1] neg_hi:[0,1]
	v_pk_fma_f32 v[36:37], v[4:5], v[78:79], v[36:37] op_sel_hi:[1,0,1]
	v_pk_add_f32 v[98:99], v[6:7], v[86:87] neg_lo:[0,1] neg_hi:[0,1]
	v_pk_fma_f32 v[36:37], v[6:7], v[78:79], v[36:37] op_sel:[0,1,0] op_sel_hi:[1,1,1]
	v_pk_fma_f32 v[0:1], v[92:93], v[40:41], v[86:87] op_sel_hi:[1,0,1]
	v_pk_fma_f32 v[2:3], v[94:95], v[40:41], v[86:87] op_sel:[0,1,0] op_sel_hi:[1,1,1]
	v_pk_fma_f32 v[4:5], v[96:97], v[42:43], v[86:87] op_sel_hi:[1,0,1]
	v_pk_fma_f32 v[6:7], v[98:99], v[42:43], v[86:87] op_sel:[0,1,0] op_sel_hi:[1,1,1]
	v_pk_mul_f32 v[38:39], v[0:1], v[44:45] op_sel_hi:[1,0]
	v_pk_fma_f32 v[38:39], v[2:3], v[44:45], v[38:39] op_sel:[0,1,0] op_sel_hi:[1,1,1]
	v_pk_fma_f32 v[38:39], v[4:5], v[46:47], v[38:39] op_sel_hi:[1,0,1]
	v_pk_fma_f32 v[38:39], v[6:7], v[46:47], v[38:39] op_sel:[0,1,0] op_sel_hi:[1,1,1]
	s_nop 1
	v_permlane16_swap_b32_e32 v8, v24
	v_permlane16_swap_b32_e32 v9, v25
	v_permlane16_swap_b32_e32 v10, v26
	v_permlane16_swap_b32_e32 v11, v27
	v_permlane16_swap_b32_e32 v12, v28
	v_permlane16_swap_b32_e32 v13, v29
	v_permlane16_swap_b32_e32 v14, v30
	v_permlane16_swap_b32_e32 v15, v31
	v_permlane16_swap_b32_e32 v16, v32
	v_permlane16_swap_b32_e32 v17, v33
	v_permlane16_swap_b32_e32 v18, v34
	v_permlane16_swap_b32_e32 v19, v35
	v_permlane16_swap_b32_e32 v20, v36
	v_permlane16_swap_b32_e32 v21, v37
	v_permlane16_swap_b32_e32 v22, v38
	v_permlane16_swap_b32_e32 v23, v39
	v_pk_add_f32 v[8:9], v[8:9], v[24:25]
	v_pk_add_f32 v[10:11], v[10:11], v[26:27]
	v_pk_add_f32 v[12:13], v[12:13], v[28:29]
	v_pk_add_f32 v[14:15], v[14:15], v[30:31]
	v_pk_add_f32 v[16:17], v[16:17], v[32:33]
	v_pk_add_f32 v[18:19], v[18:19], v[34:35]
	v_pk_add_f32 v[20:21], v[20:21], v[36:37]
	v_pk_add_f32 v[22:23], v[22:23], v[38:39]
	s_nop 1
	v_permlane32_swap_b32_e32 v8, v16
	v_permlane32_swap_b32_e32 v9, v17
	v_permlane32_swap_b32_e32 v10, v18
	v_permlane32_swap_b32_e32 v11, v19
	v_permlane32_swap_b32_e32 v12, v20
	v_permlane32_swap_b32_e32 v13, v21
	v_permlane32_swap_b32_e32 v14, v22
	v_permlane32_swap_b32_e32 v15, v23
	v_pk_add_f32 v[8:9], v[8:9], v[16:17]
	v_pk_add_f32 v[10:11], v[10:11], v[18:19]
	v_pk_add_f32 v[12:13], v[12:13], v[20:21]
	v_pk_add_f32 v[14:15], v[14:15], v[22:23]
	ds_write2_b32 v141, v8, v9 offset1:16
	ds_write2_b32 v142, v10, v11 offset1:16
	ds_write2_b32 v143, v12, v13 offset1:16
	ds_write2_b32 v144, v14, v15 offset1:16
	s_sub_u32 s15, s15, 1
	s_waitcnt lgkmcnt(0)
	s_barrier
	ds_read2_b32 v[104:105], v149 offset0:0 offset1:32
	ds_read2_b32 v[106:107], v149 offset0:64 offset1:96
	ds_read2_b32 v[108:109], v149 offset0:128 offset1:160
	ds_read2_b32 v[110:111], v149 offset0:192 offset1:224
	s_waitcnt vmcnt(7)
	v_lshlrev_b32_e32 v180, 16, v122
	v_and_b32_e32 v181, s69, v122
	v_lshlrev_b32_e32 v182, 16, v123
	v_and_b32_e32 v183, s69, v123
	s_cmp_eq_u32 s14, 0
	s_cbranch_scc1 .Lgla_st_join_3
	v_mul_f32_e32 v180, 0x3fb8aa3b, v180
	v_mul_f32_e32 v181, 0x3fb8aa3b, v181
	v_mul_f32_e32 v182, 0x3fb8aa3b, v182
	v_mul_f32_e32 v183, 0x3fb8aa3b, v183
	v_exp_f32_e32 v180, v180
	v_exp_f32_e32 v181, v181
	v_exp_f32_e32 v182, v182
	v_exp_f32_e32 v183, v183

.Lgla_st_nosc_3:
	ds_write_b128 v139, v[180:183] offset:8192
	ds_write_b128 v139, v[184:187] offset:16384
	ds_write2_b32 v140, v188, v189 offset1:4
	global_load_dwordx2 v[120:121], v130, s[8:9]
	global_load_dwordx2 v[122:123], v130, s[8:9] offset:1024
	global_load_dword v124, v131, s[8:9]
	s_add_u32 s8, s8, 0x34000
	s_addc_u32 s9, s9, 0
	s_waitcnt lgkmcnt(3)
	v_add_f32_e32 v112, v104, v105
	v_add_f32_e32 v112, v112, v106
	v_add_f32_e32 v112, v112, v107
	v_add_f32_e32 v112, v112, v108
	v_add_f32_e32 v112, v112, v109
	v_add_f32_e32 v112, v112, v110
	v_add_f32_e32 v112, v112, v111
	v_mul_f32_e32 v113, v112, v112
	v_cvt_pk_bf16_f32 v116, v112, v129
	v_mov_b32_e32 v117, v112
	v_mov_b32_e32 v118, v113
	global_store_short v132, v116, s[10:11]
	s_nop 1
	v_permlane16_swap_b32_e32 v112, v117
	v_permlane16_swap_b32_e32 v113, v118
	v_add_f32_e32 v112, v112, v117
	v_add_f32_e32 v113, v113, v118
	s_nop 1
	v_add_f32_dpp v112, v112, v112 row_ror:8 row_mask:0xf bank_mask:0xf
	v_add_f32_dpp v113, v113, v113 row_ror:8 row_mask:0xf bank_mask:0xf
	s_nop 1
	v_add_f32_dpp v112, v112, v112 row_ror:4 row_mask:0xf bank_mask:0xf
	v_add_f32_dpp v113, v113, v113 row_ror:4 row_mask:0xf bank_mask:0xf
	s_nop 1
	v_add_f32_dpp v112, v112, v112 row_ror:2 row_mask:0xf bank_mask:0xf
	v_add_f32_dpp v113, v113, v113 row_ror:2 row_mask:0xf bank_mask:0xf
	s_nop 1
	v_add_f32_dpp v112, v112, v112 row_ror:1 row_mask:0xf bank_mask:0xf
	v_add_f32_dpp v113, v113, v113 row_ror:1 row_mask:0xf bank_mask:0xf
	v_mov_b32_e32 v114, 0
	v_mov_b32_e32 v115, 0
	s_mov_b64 exec, s[18:19]
	global_store_dwordx4 v133, v[112:115], s[12:13]
	s_mov_b64 exec, -1
	s_cmp_eq_u32 s15, 512
	s_cselect_b32 s20, 0, 0x10000
	s_cselect_b32 s21, 0, 0x1000
	s_add_u32 s10, s10, s20
	s_addc_u32 s11, s11, 0
	s_add_u32 s12, s12, s21
	s_addc_u32 s13, s13, 0
	ds_read_b128 v[80:83], v135 offset:57344
	ds_read_b128 v[40:43], v134 offset:40960
	ds_read_b128 v[44:47], v134 offset:49152
	ds_read_b128 v[48:51], v134 offset:41472
	ds_read_b128 v[52:55], v134 offset:49664
	ds_read_b128 v[84:87], v135 offset:57600
	ds_read_b128 v[56:59], v134 offset:41984
	ds_read_b128 v[60:63], v134 offset:50176
	ds_read_b128 v[64:67], v134 offset:42496
	ds_read_b128 v[68:71], v134 offset:50688
	s_waitcnt lgkmcnt(7)
	v_pk_add_f32 v[92:93], v[0:1], v[80:81] neg_lo:[0,1] neg_hi:[0,1]
	v_pk_add_f32 v[94:95], v[2:3], v[80:81] neg_lo:[0,1] neg_hi:[0,1]
	v_pk_add_f32 v[96:97], v[4:5], v[80:81] neg_lo:[0,1] neg_hi:[0,1]
	v_pk_add_f32 v[98:99], v[6:7], v[80:81] neg_lo:[0,1] neg_hi:[0,1]
	v_pk_fma_f32 v[0:1], v[92:93], v[40:41], v[80:81] op_sel_hi:[1,0,1]
	v_pk_fma_f32 v[2:3], v[94:95], v[40:41], v[80:81] op_sel:[0,1,0] op_sel_hi:[1,1,1]
	v_pk_fma_f32 v[4:5], v[96:97], v[42:43], v[80:81] op_sel_hi:[1,0,1]
	v_pk_fma_f32 v[6:7], v[98:99], v[42:43], v[80:81] op_sel:[0,1,0] op_sel_hi:[1,1,1]
	ds_read_b128 v[88:91], v135 offset:57856
	ds_read_b128 v[72:75], v134 offset:43008
	ds_read_b128 v[76:79], v134 offset:51200
	s_waitcnt lgkmcnt(8)
	v_pk_add_f32 v[92:93], v[0:1], v[82:83] neg_lo:[0,1] neg_hi:[0,1]
	v_pk_mul_f32 v[8:9], v[0:1], v[44:45] op_sel_hi:[1,0]
	v_pk_add_f32 v[94:95], v[2:3], v[82:83] neg_lo:[0,1] neg_hi:[0,1]
	v_pk_fma_f32 v[8:9], v[2:3], v[44:45], v[8:9] op_sel:[0,1,0] op_sel_hi:[1,1,1]
	v_pk_add_f32 v[96:97], v[4:5], v[82:83] neg_lo:[0,1] neg_hi:[0,1]
	v_pk_fma_f32 v[8:9], v[4:5], v[46:47], v[8:9] op_sel_hi:[1,0,1]
	v_pk_add_f32 v[98:99], v[6:7], v[82:83] neg_lo:[0,1] neg_hi:[0,1]
	v_pk_fma_f32 v[8:9], v[6:7], v[46:47], v[8:9] op_sel:[0,1,0] op_sel_hi:[1,1,1]
	v_pk_fma_f32 v[0:1], v[92:93], v[48:49], v[82:83] op_sel_hi:[1,0,1]
	v_pk_fma_f32 v[2:3], v[94:95], v[48:49], v[82:83] op_sel:[0,1,0] op_sel_hi:[1,1,1]
	v_pk_fma_f32 v[4:5], v[96:97], v[50:51], v[82:83] op_sel_hi:[1,0,1]
	v_pk_fma_f32 v[6:7], v[98:99], v[50:51], v[82:83] op_sel:[0,1,0] op_sel_hi:[1,1,1]
	ds_read_b128 v[40:43], v134 offset:43520
	ds_read_b128 v[44:47], v134 offset:51712
	s_waitcnt lgkmcnt(7)
	v_pk_add_f32 v[92:93], v[0:1], v[84:85] neg_lo:[0,1] neg_hi:[0,1]
	v_pk_mul_f32 v[10:11], v[0:1], v[52:53] op_sel_hi:[1,0]
	v_pk_add_f32 v[94:95], v[2:3], v[84:85] neg_lo:[0,1] neg_hi:[0,1]
	v_pk_fma_f32 v[10:11], v[2:3], v[52:53], v[10:11] op_sel:[0,1,0] op_sel_hi:[1,1,1]
	v_pk_add_f32 v[96:97], v[4:5], v[84:85] neg_lo:[0,1] neg_hi:[0,1]
	v_pk_fma_f32 v[10:11], v[4:5], v[54:55], v[10:11] op_sel_hi:[1,0,1]
	v_pk_add_f32 v[98:99], v[6:7], v[84:85] neg_lo:[0,1] neg_hi:[0,1]
	v_pk_fma_f32 v[10:11], v[6:7], v[54:55], v[10:11] op_sel:[0,1,0] op_sel_hi:[1,1,1]
	v_pk_fma_f32 v[0:1], v[92:93], v[56:57], v[84:85] op_sel_hi:[1,0,1]
	v_pk_fma_f32 v[2:3], v[94:95], v[56:57], v[84:85] op_sel:[0,1,0] op_sel_hi:[1,1,1]
	v_pk_fma_f32 v[4:5], v[96:97], v[58:59], v[84:85] op_sel_hi:[1,0,1]
	v_pk_fma_f32 v[6:7], v[98:99], v[58:59], v[84:85] op_sel:[0,1,0] op_sel_hi:[1,1,1]
	ds_read_b128 v[80:83], v135 offset:58112
	ds_read_b128 v[48:51], v134 offset:44032
	ds_read_b128 v[52:55], v134 offset:52224
	s_waitcnt lgkmcnt(8)
	v_pk_add_f32 v[92:93], v[0:1], v[86:87] neg_lo:[0,1] neg_hi:[0,1]
	v_pk_mul_f32 v[12:13], v[0:1], v[60:61] op_sel_hi:[1,0]
	v_pk_add_f32 v[94:95], v[2:3], v[86:87] neg_lo:[0,1] neg_hi:[0,1]
	v_pk_fma_f32 v[12:13], v[2:3], v[60:61], v[12:13] op_sel:[0,1,0] op_sel_hi:[1,1,1]
	v_pk_add_f32 v[96:97], v[4:5], v[86:87] neg_lo:[0,1] neg_hi:[0,1]
	v_pk_fma_f32 v[12:13], v[4:5], v[62:63], v[12:13] op_sel_hi:[1,0,1]
	v_pk_add_f32 v[98:99], v[6:7], v[86:87] neg_lo:[0,1] neg_hi:[0,1]
	v_pk_fma_f32 v[12:13], v[6:7], v[62:63], v[12:13] op_sel:[0,1,0] op_sel_hi:[1,1,1]
	v_pk_fma_f32 v[0:1], v[92:93], v[64:65], v[86:87] op_sel_hi:[1,0,1]
	v_pk_fma_f32 v[2:3], v[94:95], v[64:65], v[86:87] op_sel:[0,1,0] op_sel_hi:[1,1,1]
	v_pk_fma_f32 v[4:5], v[96:97], v[66:67], v[86:87] op_sel_hi:[1,0,1]
	v_pk_fma_f32 v[6:7], v[98:99], v[66:67], v[86:87] op_sel:[0,1,0] op_sel_hi:[1,1,1]
	ds_read_b128 v[56:59], v134 offset:44544
	ds_read_b128 v[60:63], v134 offset:52736
	s_waitcnt lgkmcnt(7)
	v_pk_add_f32 v[92:93], v[0:1], v[88:89] neg_lo:[0,1] neg_hi:[0,1]
	v_pk_mul_f32 v[14:15], v[0:1], v[68:69] op_sel_hi:[1,0]
	v_pk_add_f32 v[94:95], v[2:3], v[88:89] neg_lo:[0,1] neg_hi:[0,1]
	v_pk_fma_f32 v[14:15], v[2:3], v[68:69], v[14:15] op_sel:[0,1,0] op_sel_hi:[1,1,1]
	v_pk_add_f32 v[96:97], v[4:5], v[88:89] neg_lo:[0,1] neg_hi:[0,1]
	v_pk_fma_f32 v[14:15], v[4:5], v[70:71], v[14:15] op_sel_hi:[1,0,1]
	v_pk_add_f32 v[98:99], v[6:7], v[88:89] neg_lo:[0,1] neg_hi:[0,1]
	v_pk_fma_f32 v[14:15], v[6:7], v[70:71], v[14:15] op_sel:[0,1,0] op_sel_hi:[1,1,1]
	v_pk_fma_f32 v[0:1], v[92:93], v[72:73], v[88:89] op_sel_hi:[1,0,1]
	v_pk_fma_f32 v[2:3], v[94:95], v[72:73], v[88:89] op_sel:[0,1,0] op_sel_hi:[1,1,1]
	v_pk_fma_f32 v[4:5], v[96:97], v[74:75], v[88:89] op_sel_hi:[1,0,1]
	v_pk_fma_f32 v[6:7], v[98:99], v[74:75], v[88:89] op_sel:[0,1,0] op_sel_hi:[1,1,1]
	ds_read_b128 v[84:87], v135 offset:58368
	ds_read_b128 v[64:67], v134 offset:45056
	ds_read_b128 v[68:71], v134 offset:53248
	s_waitcnt lgkmcnt(8)
	v_pk_add_f32 v[92:93], v[0:1], v[90:91] neg_lo:[0,1] neg_hi:[0,1]
	v_pk_mul_f32 v[16:17], v[0:1], v[76:77] op_sel_hi:[1,0]
	v_pk_add_f32 v[94:95], v[2:3], v[90:91] neg_lo:[0,1] neg_hi:[0,1]
	v_pk_fma_f32 v[16:17], v[2:3], v[76:77], v[16:17] op_sel:[0,1,0] op_sel_hi:[1,1,1]
	v_pk_add_f32 v[96:97], v[4:5], v[90:91] neg_lo:[0,1] neg_hi:[0,1]
	v_pk_fma_f32 v[16:17], v[4:5], v[78:79], v[16:17] op_sel_hi:[1,0,1]
	v_pk_add_f32 v[98:99], v[6:7], v[90:91] neg_lo:[0,1] neg_hi:[0,1]
	v_pk_fma_f32 v[16:17], v[6:7], v[78:79], v[16:17] op_sel:[0,1,0] op_sel_hi:[1,1,1]
	v_pk_fma_f32 v[0:1], v[92:93], v[40:41], v[90:91] op_sel_hi:[1,0,1]
	v_pk_fma_f32 v[2:3], v[94:95], v[40:41], v[90:91] op_sel:[0,1,0] op_sel_hi:[1,1,1]
	v_pk_fma_f32 v[4:5], v[96:97], v[42:43], v[90:91] op_sel_hi:[1,0,1]
	v_pk_fma_f32 v[6:7], v[98:99], v[42:43], v[90:91] op_sel:[0,1,0] op_sel_hi:[1,1,1]
	ds_read_b128 v[72:75], v134 offset:45568
	ds_read_b128 v[76:79], v134 offset:53760
	s_waitcnt lgkmcnt(7)
	v_pk_add_f32 v[92:93], v[0:1], v[80:81] neg_lo:[0,1] neg_hi:[0,1]
	v_pk_mul_f32 v[18:19], v[0:1], v[44:45] op_sel_hi:[1,0]
	v_pk_add_f32 v[94:95], v[2:3], v[80:81] neg_lo:[0,1] neg_hi:[0,1]
	v_pk_fma_f32 v[18:19], v[2:3], v[44:45], v[18:19] op_sel:[0,1,0] op_sel_hi:[1,1,1]
	v_pk_add_f32 v[96:97], v[4:5], v[80:81] neg_lo:[0,1] neg_hi:[0,1]
	v_pk_fma_f32 v[18:19], v[4:5], v[46:47], v[18:19] op_sel_hi:[1,0,1]
	v_pk_add_f32 v[98:99], v[6:7], v[80:81] neg_lo:[0,1] neg_hi:[0,1]
	v_pk_fma_f32 v[18:19], v[6:7], v[46:47], v[18:19] op_sel:[0,1,0] op_sel_hi:[1,1,1]
	v_pk_fma_f32 v[0:1], v[92:93], v[48:49], v[80:81] op_sel_hi:[1,0,1]
	v_pk_fma_f32 v[2:3], v[94:95], v[48:49], v[80:81] op_sel:[0,1,0] op_sel_hi:[1,1,1]
	v_pk_fma_f32 v[4:5], v[96:97], v[50:51], v[80:81] op_sel_hi:[1,0,1]
	v_pk_fma_f32 v[6:7], v[98:99], v[50:51], v[80:81] op_sel:[0,1,0] op_sel_hi:[1,1,1]
	ds_read_b128 v[88:91], v135 offset:58624
	ds_read_b128 v[40:43], v134 offset:46080
	ds_read_b128 v[44:47], v134 offset:54272
	s_waitcnt lgkmcnt(8)
	v_pk_add_f32 v[92:93], v[0:1], v[82:83] neg_lo:[0,1] neg_hi:[0,1]
	v_pk_mul_f32 v[20:21], v[0:1], v[52:53] op_sel_hi:[1,0]
	v_pk_add_f32 v[94:95], v[2:3], v[82:83] neg_lo:[0,1] neg_hi:[0,1]
	v_pk_fma_f32 v[20:21], v[2:3], v[52:53], v[20:21] op_sel:[0,1,0] op_sel_hi:[1,1,1]
	v_pk_add_f32 v[96:97], v[4:5], v[82:83] neg_lo:[0,1] neg_hi:[0,1]
	v_pk_fma_f32 v[20:21], v[4:5], v[54:55], v[20:21] op_sel_hi:[1,0,1]
	v_pk_add_f32 v[98:99], v[6:7], v[82:83] neg_lo:[0,1] neg_hi:[0,1]
	v_pk_fma_f32 v[20:21], v[6:7], v[54:55], v[20:21] op_sel:[0,1,0] op_sel_hi:[1,1,1]
	v_pk_fma_f32 v[0:1], v[92:93], v[56:57], v[82:83] op_sel_hi:[1,0,1]
	v_pk_fma_f32 v[2:3], v[94:95], v[56:57], v[82:83] op_sel:[0,1,0] op_sel_hi:[1,1,1]
	v_pk_fma_f32 v[4:5], v[96:97], v[58:59], v[82:83] op_sel_hi:[1,0,1]
	v_pk_fma_f32 v[6:7], v[98:99], v[58:59], v[82:83] op_sel:[0,1,0] op_sel_hi:[1,1,1]
	ds_read_b128 v[48:51], v134 offset:46592
	ds_read_b128 v[52:55], v134 offset:54784
	s_waitcnt lgkmcnt(7)
	v_pk_add_f32 v[92:93], v[0:1], v[84:85] neg_lo:[0,1] neg_hi:[0,1]
	v_pk_mul_f32 v[22:23], v[0:1], v[60:61] op_sel_hi:[1,0]
	v_pk_add_f32 v[94:95], v[2:3], v[84:85] neg_lo:[0,1] neg_hi:[0,1]
	v_pk_fma_f32 v[22:23], v[2:3], v[60:61], v[22:23] op_sel:[0,1,0] op_sel_hi:[1,1,1]
	v_pk_add_f32 v[96:97], v[4:5], v[84:85] neg_lo:[0,1] neg_hi:[0,1]
	v_pk_fma_f32 v[22:23], v[4:5], v[62:63], v[22:23] op_sel_hi:[1,0,1]
	v_pk_add_f32 v[98:99], v[6:7], v[84:85] neg_lo:[0,1] neg_hi:[0,1]
	v_pk_fma_f32 v[22:23], v[6:7], v[62:63], v[22:23] op_sel:[0,1,0] op_sel_hi:[1,1,1]
	v_pk_fma_f32 v[0:1], v[92:93], v[64:65], v[84:85] op_sel_hi:[1,0,1]
	v_pk_fma_f32 v[2:3], v[94:95], v[64:65], v[84:85] op_sel:[0,1,0] op_sel_hi:[1,1,1]
	v_pk_fma_f32 v[4:5], v[96:97], v[66:67], v[84:85] op_sel_hi:[1,0,1]
	v_pk_fma_f32 v[6:7], v[98:99], v[66:67], v[84:85] op_sel:[0,1,0] op_sel_hi:[1,1,1]
	ds_read_b128 v[80:83], v135 offset:58880
	ds_read_b128 v[56:59], v134 offset:47104
	ds_read_b128 v[60:63], v134 offset:55296
	s_waitcnt lgkmcnt(8)
	v_pk_add_f32 v[92:93], v[0:1], v[86:87] neg_lo:[0,1] neg_hi:[0,1]
	v_pk_mul_f32 v[24:25], v[0:1], v[68:69] op_sel_hi:[1,0]
	v_pk_add_f32 v[94:95], v[2:3], v[86:87] neg_lo:[0,1] neg_hi:[0,1]
	v_pk_fma_f32 v[24:25], v[2:3], v[68:69], v[24:25] op_sel:[0,1,0] op_sel_hi:[1,1,1]
	v_pk_add_f32 v[96:97], v[4:5], v[86:87] neg_lo:[0,1] neg_hi:[0,1]
	v_pk_fma_f32 v[24:25], v[4:5], v[70:71], v[24:25] op_sel_hi:[1,0,1]
	v_pk_add_f32 v[98:99], v[6:7], v[86:87] neg_lo:[0,1] neg_hi:[0,1]
	v_pk_fma_f32 v[24:25], v[6:7], v[70:71], v[24:25] op_sel:[0,1,0] op_sel_hi:[1,1,1]
	v_pk_fma_f32 v[0:1], v[92:93], v[72:73], v[86:87] op_sel_hi:[1,0,1]
	v_pk_fma_f32 v[2:3], v[94:95], v[72:73], v[86:87] op_sel:[0,1,0] op_sel_hi:[1,1,1]
	v_pk_fma_f32 v[4:5], v[96:97], v[74:75], v[86:87] op_sel_hi:[1,0,1]
	v_pk_fma_f32 v[6:7], v[98:99], v[74:75], v[86:87] op_sel:[0,1,0] op_sel_hi:[1,1,1]
	ds_read_b128 v[64:67], v134 offset:47616
	ds_read_b128 v[68:71], v134 offset:55808
	s_waitcnt lgkmcnt(7)
	v_pk_add_f32 v[92:93], v[0:1], v[88:89] neg_lo:[0,1] neg_hi:[0,1]
	v_pk_mul_f32 v[26:27], v[0:1], v[76:77] op_sel_hi:[1,0]
	v_pk_add_f32 v[94:95], v[2:3], v[88:89] neg_lo:[0,1] neg_hi:[0,1]
	v_pk_fma_f32 v[26:27], v[2:3], v[76:77], v[26:27] op_sel:[0,1,0] op_sel_hi:[1,1,1]
	v_pk_add_f32 v[96:97], v[4:5], v[88:89] neg_lo:[0,1] neg_hi:[0,1]
	v_pk_fma_f32 v[26:27], v[4:5], v[78:79], v[26:27] op_sel_hi:[1,0,1]
	v_pk_add_f32 v[98:99], v[6:7], v[88:89] neg_lo:[0,1] neg_hi:[0,1]
	v_pk_fma_f32 v[26:27], v[6:7], v[78:79], v[26:27] op_sel:[0,1,0] op_sel_hi:[1,1,1]
	v_pk_fma_f32 v[0:1], v[92:93], v[40:41], v[88:89] op_sel_hi:[1,0,1]
	v_pk_fma_f32 v[2:3], v[94:95], v[40:41], v[88:89] op_sel:[0,1,0] op_sel_hi:[1,1,1]
	v_pk_fma_f32 v[4:5], v[96:97], v[42:43], v[88:89] op_sel_hi:[1,0,1]
	v_pk_fma_f32 v[6:7], v[98:99], v[42:43], v[88:89] op_sel:[0,1,0] op_sel_hi:[1,1,1]
	ds_read_b128 v[84:87], v135 offset:59136
	ds_read_b128 v[72:75], v134 offset:48128
	ds_read_b128 v[76:79], v134 offset:56320
	s_waitcnt lgkmcnt(8)
	v_pk_add_f32 v[92:93], v[0:1], v[90:91] neg_lo:[0,1] neg_hi:[0,1]
	v_pk_mul_f32 v[28:29], v[0:1], v[44:45] op_sel_hi:[1,0]
	v_pk_add_f32 v[94:95], v[2:3], v[90:91] neg_lo:[0,1] neg_hi:[0,1]
	v_pk_fma_f32 v[28:29], v[2:3], v[44:45], v[28:29] op_sel:[0,1,0] op_sel_hi:[1,1,1]
	v_pk_add_f32 v[96:97], v[4:5], v[90:91] neg_lo:[0,1] neg_hi:[0,1]
	v_pk_fma_f32 v[28:29], v[4:5], v[46:47], v[28:29] op_sel_hi:[1,0,1]
	v_pk_add_f32 v[98:99], v[6:7], v[90:91] neg_lo:[0,1] neg_hi:[0,1]
	v_pk_fma_f32 v[28:29], v[6:7], v[46:47], v[28:29] op_sel:[0,1,0] op_sel_hi:[1,1,1]
	v_pk_fma_f32 v[0:1], v[92:93], v[48:49], v[90:91] op_sel_hi:[1,0,1]
	v_pk_fma_f32 v[2:3], v[94:95], v[48:49], v[90:91] op_sel:[0,1,0] op_sel_hi:[1,1,1]
	v_pk_fma_f32 v[4:5], v[96:97], v[50:51], v[90:91] op_sel_hi:[1,0,1]
	v_pk_fma_f32 v[6:7], v[98:99], v[50:51], v[90:91] op_sel:[0,1,0] op_sel_hi:[1,1,1]
	ds_read_b128 v[40:43], v134 offset:48640
	ds_read_b128 v[44:47], v134 offset:56832
	s_waitcnt lgkmcnt(7)
	v_pk_add_f32 v[92:93], v[0:1], v[80:81] neg_lo:[0,1] neg_hi:[0,1]
	v_pk_mul_f32 v[30:31], v[0:1], v[52:53] op_sel_hi:[1,0]
	v_pk_add_f32 v[94:95], v[2:3], v[80:81] neg_lo:[0,1] neg_hi:[0,1]
	v_pk_fma_f32 v[30:31], v[2:3], v[52:53], v[30:31] op_sel:[0,1,0] op_sel_hi:[1,1,1]
	v_pk_add_f32 v[96:97], v[4:5], v[80:81] neg_lo:[0,1] neg_hi:[0,1]
	v_pk_fma_f32 v[30:31], v[4:5], v[54:55], v[30:31] op_sel_hi:[1,0,1]
	v_pk_add_f32 v[98:99], v[6:7], v[80:81] neg_lo:[0,1] neg_hi:[0,1]
	v_pk_fma_f32 v[30:31], v[6:7], v[54:55], v[30:31] op_sel:[0,1,0] op_sel_hi:[1,1,1]
	v_pk_fma_f32 v[0:1], v[92:93], v[56:57], v[80:81] op_sel_hi:[1,0,1]
	v_pk_fma_f32 v[2:3], v[94:95], v[56:57], v[80:81] op_sel:[0,1,0] op_sel_hi:[1,1,1]
	v_pk_fma_f32 v[4:5], v[96:97], v[58:59], v[80:81] op_sel_hi:[1,0,1]
	v_pk_fma_f32 v[6:7], v[98:99], v[58:59], v[80:81] op_sel:[0,1,0] op_sel_hi:[1,1,1]
	s_waitcnt lgkmcnt(5)
	v_pk_add_f32 v[92:93], v[0:1], v[82:83] neg_lo:[0,1] neg_hi:[0,1]
	v_pk_mul_f32 v[32:33], v[0:1], v[60:61] op_sel_hi:[1,0]
	v_pk_add_f32 v[94:95], v[2:3], v[82:83] neg_lo:[0,1] neg_hi:[0,1]
	v_pk_fma_f32 v[32:33], v[2:3], v[60:61], v[32:33] op_sel:[0,1,0] op_sel_hi:[1,1,1]
	v_pk_add_f32 v[96:97], v[4:5], v[82:83] neg_lo:[0,1] neg_hi:[0,1]
	v_pk_fma_f32 v[32:33], v[4:5], v[62:63], v[32:33] op_sel_hi:[1,0,1]
	v_pk_add_f32 v[98:99], v[6:7], v[82:83] neg_lo:[0,1] neg_hi:[0,1]
	v_pk_fma_f32 v[32:33], v[6:7], v[62:63], v[32:33] op_sel:[0,1,0] op_sel_hi:[1,1,1]
	v_pk_fma_f32 v[0:1], v[92:93], v[64:65], v[82:83] op_sel_hi:[1,0,1]
	v_pk_fma_f32 v[2:3], v[94:95], v[64:65], v[82:83] op_sel:[0,1,0] op_sel_hi:[1,1,1]
	v_pk_fma_f32 v[4:5], v[96:97], v[66:67], v[82:83] op_sel_hi:[1,0,1]
	v_pk_fma_f32 v[6:7], v[98:99], v[66:67], v[82:83] op_sel:[0,1,0] op_sel_hi:[1,1,1]
	s_waitcnt lgkmcnt(2)
	v_pk_add_f32 v[92:93], v[0:1], v[84:85] neg_lo:[0,1] neg_hi:[0,1]
	v_pk_mul_f32 v[34:35], v[0:1], v[68:69] op_sel_hi:[1,0]
	v_pk_add_f32 v[94:95], v[2:3], v[84:85] neg_lo:[0,1] neg_hi:[0,1]
	v_pk_fma_f32 v[34:35], v[2:3], v[68:69], v[34:35] op_sel:[0,1,0] op_sel_hi:[1,1,1]
	v_pk_add_f32 v[96:97], v[4:5], v[84:85] neg_lo:[0,1] neg_hi:[0,1]
	v_pk_fma_f32 v[34:35], v[4:5], v[70:71], v[34:35] op_sel_hi:[1,0,1]
	v_pk_add_f32 v[98:99], v[6:7], v[84:85] neg_lo:[0,1] neg_hi:[0,1]
	v_pk_fma_f32 v[34:35], v[6:7], v[70:71], v[34:35] op_sel:[0,1,0] op_sel_hi:[1,1,1]
	v_pk_fma_f32 v[0:1], v[92:93], v[72:73], v[84:85] op_sel_hi:[1,0,1]
	v_pk_fma_f32 v[2:3], v[94:95], v[72:73], v[84:85] op_sel:[0,1,0] op_sel_hi:[1,1,1]
	v_pk_fma_f32 v[4:5], v[96:97], v[74:75], v[84:85] op_sel_hi:[1,0,1]
	v_pk_fma_f32 v[6:7], v[98:99], v[74:75], v[84:85] op_sel:[0,1,0] op_sel_hi:[1,1,1]
	s_waitcnt lgkmcnt(0)
	v_pk_add_f32 v[92:93], v[0:1], v[86:87] neg_lo:[0,1] neg_hi:[0,1]
	v_pk_mul_f32 v[36:37], v[0:1], v[76:77] op_sel_hi:[1,0]
	v_pk_add_f32 v[94:95], v[2:3], v[86:87] neg_lo:[0,1] neg_hi:[0,1]
	v_pk_fma_f32 v[36:37], v[2:3], v[76:77], v[36:37] op_sel:[0,1,0] op_sel_hi:[1,1,1]
	v_pk_add_f32 v[96:97], v[4:5], v[86:87] neg_lo:[0,1] neg_hi:[0,1]
	v_pk_fma_f32 v[36:37], v[4:5], v[78:79], v[36:37] op_sel_hi:[1,0,1]
	v_pk_add_f32 v[98:99], v[6:7], v[86:87] neg_lo:[0,1] neg_hi:[0,1]
	v_pk_fma_f32 v[36:37], v[6:7], v[78:79], v[36:37] op_sel:[0,1,0] op_sel_hi:[1,1,1]
	v_pk_fma_f32 v[0:1], v[92:93], v[40:41], v[86:87] op_sel_hi:[1,0,1]
	v_pk_fma_f32 v[2:3], v[94:95], v[40:41], v[86:87] op_sel:[0,1,0] op_sel_hi:[1,1,1]
	v_pk_fma_f32 v[4:5], v[96:97], v[42:43], v[86:87] op_sel_hi:[1,0,1]
	v_pk_fma_f32 v[6:7], v[98:99], v[42:43], v[86:87] op_sel:[0,1,0] op_sel_hi:[1,1,1]
	v_pk_mul_f32 v[38:39], v[0:1], v[44:45] op_sel_hi:[1,0]
	v_pk_fma_f32 v[38:39], v[2:3], v[44:45], v[38:39] op_sel:[0,1,0] op_sel_hi:[1,1,1]
	v_pk_fma_f32 v[38:39], v[4:5], v[46:47], v[38:39] op_sel_hi:[1,0,1]
	v_pk_fma_f32 v[38:39], v[6:7], v[46:47], v[38:39] op_sel:[0,1,0] op_sel_hi:[1,1,1]
	s_nop 1
	v_permlane16_swap_b32_e32 v8, v24
	v_permlane16_swap_b32_e32 v9, v25
	v_permlane16_swap_b32_e32 v10, v26
	v_permlane16_swap_b32_e32 v11, v27
	v_permlane16_swap_b32_e32 v12, v28
	v_permlane16_swap_b32_e32 v13, v29
	v_permlane16_swap_b32_e32 v14, v30
	v_permlane16_swap_b32_e32 v15, v31
	v_permlane16_swap_b32_e32 v16, v32
	v_permlane16_swap_b32_e32 v17, v33
	v_permlane16_swap_b32_e32 v18, v34
	v_permlane16_swap_b32_e32 v19, v35
	v_permlane16_swap_b32_e32 v20, v36
	v_permlane16_swap_b32_e32 v21, v37
	v_permlane16_swap_b32_e32 v22, v38
	v_permlane16_swap_b32_e32 v23, v39
	v_pk_add_f32 v[8:9], v[8:9], v[24:25]
	v_pk_add_f32 v[10:11], v[10:11], v[26:27]
	v_pk_add_f32 v[12:13], v[12:13], v[28:29]
	v_pk_add_f32 v[14:15], v[14:15], v[30:31]
	v_pk_add_f32 v[16:17], v[16:17], v[32:33]
	v_pk_add_f32 v[18:19], v[18:19], v[34:35]
	v_pk_add_f32 v[20:21], v[20:21], v[36:37]
	v_pk_add_f32 v[22:23], v[22:23], v[38:39]
	s_nop 1
	v_permlane32_swap_b32_e32 v8, v16
	v_permlane32_swap_b32_e32 v9, v17
	v_permlane32_swap_b32_e32 v10, v18
	v_permlane32_swap_b32_e32 v11, v19
	v_permlane32_swap_b32_e32 v12, v20
	v_permlane32_swap_b32_e32 v13, v21
	v_permlane32_swap_b32_e32 v14, v22
	v_permlane32_swap_b32_e32 v15, v23
	v_pk_add_f32 v[8:9], v[8:9], v[16:17]
	v_pk_add_f32 v[10:11], v[10:11], v[18:19]
	v_pk_add_f32 v[12:13], v[12:13], v[20:21]
	v_pk_add_f32 v[14:15], v[14:15], v[22:23]
	ds_write2_b32 v145, v8, v9 offset1:16
	ds_write2_b32 v146, v10, v11 offset1:16
	ds_write2_b32 v147, v12, v13 offset1:16
	ds_write2_b32 v148, v14, v15 offset1:16
	s_sub_u32 s15, s15, 1
	s_waitcnt lgkmcnt(0)
	s_barrier
	s_cmp_lg_u32 s15, 0
	s_cbranch_scc1 .Lgla_loop_hgrn
	s_branch .Lgla_tail
	.p2align 6

.Lgla_st_nosc_4:
	ds_write_b128 v139, v[180:183] offset:40960
	ds_write_b128 v139, v[184:187] offset:49152
	ds_write2_b32 v153, v188, v189 offset1:4
	global_load_dwordx2 v[126:127], v130, s[8:9]
	global_load_dwordx2 v[190:191], v130, s[8:9] offset:1024
	global_load_dword v119, v131, s[8:9]
	s_add_u32 s8, s8, 0x34000
	s_addc_u32 s9, s9, 0
	s_waitcnt lgkmcnt(3)
	v_add_f32_e32 v112, v104, v105
	v_add_f32_e32 v112, v112, v106
	v_add_f32_e32 v112, v112, v107
	v_add_f32_e32 v112, v112, v108
	v_add_f32_e32 v112, v112, v109
	v_add_f32_e32 v112, v112, v110
	v_add_f32_e32 v112, v112, v111
	v_mul_f32_e32 v113, v112, v112
	v_cvt_pk_bf16_f32 v116, v112, v129
	v_mov_b32_e32 v117, v112
	v_mov_b32_e32 v118, v113
	global_store_short v132, v116, s[10:11]
	s_nop 1
	v_permlane16_swap_b32_e32 v112, v117
	v_permlane16_swap_b32_e32 v113, v118
	v_add_f32_e32 v112, v112, v117
	v_add_f32_e32 v113, v113, v118
	s_nop 1
	v_add_f32_dpp v112, v112, v112 row_ror:8 row_mask:0xf bank_mask:0xf
	v_add_f32_dpp v113, v113, v113 row_ror:8 row_mask:0xf bank_mask:0xf
	s_nop 1
	v_add_f32_dpp v112, v112, v112 row_ror:4 row_mask:0xf bank_mask:0xf
	v_add_f32_dpp v113, v113, v113 row_ror:4 row_mask:0xf bank_mask:0xf
	s_nop 1
	v_add_f32_dpp v112, v112, v112 row_ror:2 row_mask:0xf bank_mask:0xf
	v_add_f32_dpp v113, v113, v113 row_ror:2 row_mask:0xf bank_mask:0xf
	s_nop 1
	v_add_f32_dpp v112, v112, v112 row_ror:1 row_mask:0xf bank_mask:0xf
	v_add_f32_dpp v113, v113, v113 row_ror:1 row_mask:0xf bank_mask:0xf
	v_mov_b32_e32 v114, 0
	v_mov_b32_e32 v115, 0
	s_mov_b64 exec, s[18:19]
	global_store_dwordx4 v133, v[112:115], s[12:13]
	s_mov_b64 exec, -1
	s_cmp_eq_u32 s15, 512
	s_cselect_b32 s20, 0, 0x10000
	s_cselect_b32 s21, 0, 0x1000
	s_add_u32 s10, s10, s20
	s_addc_u32 s11, s11, 0
	s_add_u32 s12, s12, s21
	s_addc_u32 s13, s13, 0
	ds_read_b128 v[80:83], v135 offset:24576
	ds_read_b128 v[40:43], v134 offset:8192
	ds_read_b128 v[44:47], v134 offset:16384
	ds_read_b128 v[48:51], v134 offset:8704
	ds_read_b128 v[52:55], v134 offset:16896
	ds_read_b128 v[84:87], v135 offset:24832
	ds_read_b128 v[56:59], v134 offset:9216
	ds_read_b128 v[60:63], v134 offset:17408
	ds_read_b128 v[64:67], v134 offset:9728
	ds_read_b128 v[68:71], v134 offset:17920
	s_waitcnt lgkmcnt(7)
	v_pk_fma_f32 v[0:1], v[80:81], v[40:41], v[0:1] op_sel_hi:[1,0,1]
	v_pk_fma_f32 v[2:3], v[80:81], v[40:41], v[2:3] op_sel:[0,1,0] op_sel_hi:[1,1,1]
	v_pk_fma_f32 v[4:5], v[80:81], v[42:43], v[4:5] op_sel_hi:[1,0,1]
	v_pk_fma_f32 v[6:7], v[80:81], v[42:43], v[6:7] op_sel:[0,1,0] op_sel_hi:[1,1,1]
	ds_read_b128 v[88:91], v135 offset:25088
	ds_read_b128 v[72:75], v134 offset:10240
	ds_read_b128 v[76:79], v134 offset:18432
	s_waitcnt lgkmcnt(8)
	v_pk_mul_f32 v[8:9], v[0:1], v[44:45] op_sel_hi:[1,0]
	v_pk_fma_f32 v[0:1], v[82:83], v[48:49], v[0:1] op_sel_hi:[1,0,1]
	v_pk_fma_f32 v[8:9], v[2:3], v[44:45], v[8:9] op_sel:[0,1,0] op_sel_hi:[1,1,1]
	v_pk_fma_f32 v[2:3], v[82:83], v[48:49], v[2:3] op_sel:[0,1,0] op_sel_hi:[1,1,1]
	v_pk_fma_f32 v[8:9], v[4:5], v[46:47], v[8:9] op_sel_hi:[1,0,1]
	v_pk_fma_f32 v[4:5], v[82:83], v[50:51], v[4:5] op_sel_hi:[1,0,1]
	v_pk_fma_f32 v[8:9], v[6:7], v[46:47], v[8:9] op_sel:[0,1,0] op_sel_hi:[1,1,1]
	v_pk_fma_f32 v[6:7], v[82:83], v[50:51], v[6:7] op_sel:[0,1,0] op_sel_hi:[1,1,1]
	ds_read_b128 v[40:43], v134 offset:10752
	ds_read_b128 v[44:47], v134 offset:18944
	s_waitcnt lgkmcnt(7)
	v_pk_mul_f32 v[10:11], v[0:1], v[52:53] op_sel_hi:[1,0]
	v_pk_fma_f32 v[0:1], v[84:85], v[56:57], v[0:1] op_sel_hi:[1,0,1]
	v_pk_fma_f32 v[10:11], v[2:3], v[52:53], v[10:11] op_sel:[0,1,0] op_sel_hi:[1,1,1]
	v_pk_fma_f32 v[2:3], v[84:85], v[56:57], v[2:3] op_sel:[0,1,0] op_sel_hi:[1,1,1]
	v_pk_fma_f32 v[10:11], v[4:5], v[54:55], v[10:11] op_sel_hi:[1,0,1]
	v_pk_fma_f32 v[4:5], v[84:85], v[58:59], v[4:5] op_sel_hi:[1,0,1]
	v_pk_fma_f32 v[10:11], v[6:7], v[54:55], v[10:11] op_sel:[0,1,0] op_sel_hi:[1,1,1]
	v_pk_fma_f32 v[6:7], v[84:85], v[58:59], v[6:7] op_sel:[0,1,0] op_sel_hi:[1,1,1]
	ds_read_b128 v[80:83], v135 offset:25344
	ds_read_b128 v[48:51], v134 offset:11264
	ds_read_b128 v[52:55], v134 offset:19456
	s_waitcnt lgkmcnt(8)
	v_pk_mul_f32 v[12:13], v[0:1], v[60:61] op_sel_hi:[1,0]
	v_pk_fma_f32 v[0:1], v[86:87], v[64:65], v[0:1] op_sel_hi:[1,0,1]
	v_pk_fma_f32 v[12:13], v[2:3], v[60:61], v[12:13] op_sel:[0,1,0] op_sel_hi:[1,1,1]
	v_pk_fma_f32 v[2:3], v[86:87], v[64:65], v[2:3] op_sel:[0,1,0] op_sel_hi:[1,1,1]
	v_pk_fma_f32 v[12:13], v[4:5], v[62:63], v[12:13] op_sel_hi:[1,0,1]
	v_pk_fma_f32 v[4:5], v[86:87], v[66:67], v[4:5] op_sel_hi:[1,0,1]
	v_pk_fma_f32 v[12:13], v[6:7], v[62:63], v[12:13] op_sel:[0,1,0] op_sel_hi:[1,1,1]
	v_pk_fma_f32 v[6:7], v[86:87], v[66:67], v[6:7] op_sel:[0,1,0] op_sel_hi:[1,1,1]
	ds_read_b128 v[56:59], v134 offset:11776
	ds_read_b128 v[60:63], v134 offset:19968
	s_waitcnt lgkmcnt(7)
	v_pk_mul_f32 v[14:15], v[0:1], v[68:69] op_sel_hi:[1,0]
	v_pk_fma_f32 v[0:1], v[88:89], v[72:73], v[0:1] op_sel_hi:[1,0,1]
	v_pk_fma_f32 v[14:15], v[2:3], v[68:69], v[14:15] op_sel:[0,1,0] op_sel_hi:[1,1,1]
	v_pk_fma_f32 v[2:3], v[88:89], v[72:73], v[2:3] op_sel:[0,1,0] op_sel_hi:[1,1,1]
	v_pk_fma_f32 v[14:15], v[4:5], v[70:71], v[14:15] op_sel_hi:[1,0,1]
	v_pk_fma_f32 v[4:5], v[88:89], v[74:75], v[4:5] op_sel_hi:[1,0,1]
	v_pk_fma_f32 v[14:15], v[6:7], v[70:71], v[14:15] op_sel:[0,1,0] op_sel_hi:[1,1,1]
	v_pk_fma_f32 v[6:7], v[88:89], v[74:75], v[6:7] op_sel:[0,1,0] op_sel_hi:[1,1,1]
	ds_read_b128 v[84:87], v135 offset:25600
	ds_read_b128 v[64:67], v134 offset:12288
	ds_read_b128 v[68:71], v134 offset:20480
	s_waitcnt lgkmcnt(8)
	v_pk_mul_f32 v[16:17], v[0:1], v[76:77] op_sel_hi:[1,0]
	v_pk_fma_f32 v[0:1], v[90:91], v[40:41], v[0:1] op_sel_hi:[1,0,1]
	v_pk_fma_f32 v[16:17], v[2:3], v[76:77], v[16:17] op_sel:[0,1,0] op_sel_hi:[1,1,1]
	v_pk_fma_f32 v[2:3], v[90:91], v[40:41], v[2:3] op_sel:[0,1,0] op_sel_hi:[1,1,1]
	v_pk_fma_f32 v[16:17], v[4:5], v[78:79], v[16:17] op_sel_hi:[1,0,1]
	v_pk_fma_f32 v[4:5], v[90:91], v[42:43], v[4:5] op_sel_hi:[1,0,1]
	v_pk_fma_f32 v[16:17], v[6:7], v[78:79], v[16:17] op_sel:[0,1,0] op_sel_hi:[1,1,1]
	v_pk_fma_f32 v[6:7], v[90:91], v[42:43], v[6:7] op_sel:[0,1,0] op_sel_hi:[1,1,1]
	ds_read_b128 v[72:75], v134 offset:12800
	ds_read_b128 v[76:79], v134 offset:20992
	s_waitcnt lgkmcnt(7)
	v_pk_mul_f32 v[18:19], v[0:1], v[44:45] op_sel_hi:[1,0]
	v_pk_fma_f32 v[0:1], v[80:81], v[48:49], v[0:1] op_sel_hi:[1,0,1]
	v_pk_fma_f32 v[18:19], v[2:3], v[44:45], v[18:19] op_sel:[0,1,0] op_sel_hi:[1,1,1]
	v_pk_fma_f32 v[2:3], v[80:81], v[48:49], v[2:3] op_sel:[0,1,0] op_sel_hi:[1,1,1]
	v_pk_fma_f32 v[18:19], v[4:5], v[46:47], v[18:19] op_sel_hi:[1,0,1]
	v_pk_fma_f32 v[4:5], v[80:81], v[50:51], v[4:5] op_sel_hi:[1,0,1]
	v_pk_fma_f32 v[18:19], v[6:7], v[46:47], v[18:19] op_sel:[0,1,0] op_sel_hi:[1,1,1]
	v_pk_fma_f32 v[6:7], v[80:81], v[50:51], v[6:7] op_sel:[0,1,0] op_sel_hi:[1,1,1]
	ds_read_b128 v[88:91], v135 offset:25856
	ds_read_b128 v[40:43], v134 offset:13312
	ds_read_b128 v[44:47], v134 offset:21504
	s_waitcnt lgkmcnt(8)
	v_pk_mul_f32 v[20:21], v[0:1], v[52:53] op_sel_hi:[1,0]
	v_pk_fma_f32 v[0:1], v[82:83], v[56:57], v[0:1] op_sel_hi:[1,0,1]
	v_pk_fma_f32 v[20:21], v[2:3], v[52:53], v[20:21] op_sel:[0,1,0] op_sel_hi:[1,1,1]
	v_pk_fma_f32 v[2:3], v[82:83], v[56:57], v[2:3] op_sel:[0,1,0] op_sel_hi:[1,1,1]
	v_pk_fma_f32 v[20:21], v[4:5], v[54:55], v[20:21] op_sel_hi:[1,0,1]
	v_pk_fma_f32 v[4:5], v[82:83], v[58:59], v[4:5] op_sel_hi:[1,0,1]
	v_pk_fma_f32 v[20:21], v[6:7], v[54:55], v[20:21] op_sel:[0,1,0] op_sel_hi:[1,1,1]
	v_pk_fma_f32 v[6:7], v[82:83], v[58:59], v[6:7] op_sel:[0,1,0] op_sel_hi:[1,1,1]
	ds_read_b128 v[48:51], v134 offset:13824
	ds_read_b128 v[52:55], v134 offset:22016
	s_waitcnt lgkmcnt(7)
	v_pk_mul_f32 v[22:23], v[0:1], v[60:61] op_sel_hi:[1,0]
	v_pk_fma_f32 v[0:1], v[84:85], v[64:65], v[0:1] op_sel_hi:[1,0,1]
	v_pk_fma_f32 v[22:23], v[2:3], v[60:61], v[22:23] op_sel:[0,1,0] op_sel_hi:[1,1,1]
	v_pk_fma_f32 v[2:3], v[84:85], v[64:65], v[2:3] op_sel:[0,1,0] op_sel_hi:[1,1,1]
	v_pk_fma_f32 v[22:23], v[4:5], v[62:63], v[22:23] op_sel_hi:[1,0,1]
	v_pk_fma_f32 v[4:5], v[84:85], v[66:67], v[4:5] op_sel_hi:[1,0,1]
	v_pk_fma_f32 v[22:23], v[6:7], v[62:63], v[22:23] op_sel:[0,1,0] op_sel_hi:[1,1,1]
	v_pk_fma_f32 v[6:7], v[84:85], v[66:67], v[6:7] op_sel:[0,1,0] op_sel_hi:[1,1,1]
	ds_read_b128 v[80:83], v135 offset:26112
	ds_read_b128 v[56:59], v134 offset:14336
	ds_read_b128 v[60:63], v134 offset:22528
	s_waitcnt lgkmcnt(8)
	v_pk_mul_f32 v[24:25], v[0:1], v[68:69] op_sel_hi:[1,0]
	v_pk_fma_f32 v[0:1], v[86:87], v[72:73], v[0:1] op_sel_hi:[1,0,1]
	v_pk_fma_f32 v[24:25], v[2:3], v[68:69], v[24:25] op_sel:[0,1,0] op_sel_hi:[1,1,1]
	v_pk_fma_f32 v[2:3], v[86:87], v[72:73], v[2:3] op_sel:[0,1,0] op_sel_hi:[1,1,1]
	v_pk_fma_f32 v[24:25], v[4:5], v[70:71], v[24:25] op_sel_hi:[1,0,1]
	v_pk_fma_f32 v[4:5], v[86:87], v[74:75], v[4:5] op_sel_hi:[1,0,1]
	v_pk_fma_f32 v[24:25], v[6:7], v[70:71], v[24:25] op_sel:[0,1,0] op_sel_hi:[1,1,1]
	v_pk_fma_f32 v[6:7], v[86:87], v[74:75], v[6:7] op_sel:[0,1,0] op_sel_hi:[1,1,1]
	ds_read_b128 v[64:67], v134 offset:14848
	ds_read_b128 v[68:71], v134 offset:23040
	s_waitcnt lgkmcnt(7)
	v_pk_mul_f32 v[26:27], v[0:1], v[76:77] op_sel_hi:[1,0]
	v_pk_fma_f32 v[0:1], v[88:89], v[40:41], v[0:1] op_sel_hi:[1,0,1]
	v_pk_fma_f32 v[26:27], v[2:3], v[76:77], v[26:27] op_sel:[0,1,0] op_sel_hi:[1,1,1]
	v_pk_fma_f32 v[2:3], v[88:89], v[40:41], v[2:3] op_sel:[0,1,0] op_sel_hi:[1,1,1]
	v_pk_fma_f32 v[26:27], v[4:5], v[78:79], v[26:27] op_sel_hi:[1,0,1]
	v_pk_fma_f32 v[4:5], v[88:89], v[42:43], v[4:5] op_sel_hi:[1,0,1]
	v_pk_fma_f32 v[26:27], v[6:7], v[78:79], v[26:27] op_sel:[0,1,0] op_sel_hi:[1,1,1]
	v_pk_fma_f32 v[6:7], v[88:89], v[42:43], v[6:7] op_sel:[0,1,0] op_sel_hi:[1,1,1]
	ds_read_b128 v[84:87], v135 offset:26368
	ds_read_b128 v[72:75], v134 offset:15360
	ds_read_b128 v[76:79], v134 offset:23552
	s_waitcnt lgkmcnt(8)
	v_pk_mul_f32 v[28:29], v[0:1], v[44:45] op_sel_hi:[1,0]
	v_pk_fma_f32 v[0:1], v[90:91], v[48:49], v[0:1] op_sel_hi:[1,0,1]
	v_pk_fma_f32 v[28:29], v[2:3], v[44:45], v[28:29] op_sel:[0,1,0] op_sel_hi:[1,1,1]
	v_pk_fma_f32 v[2:3], v[90:91], v[48:49], v[2:3] op_sel:[0,1,0] op_sel_hi:[1,1,1]
	v_pk_fma_f32 v[28:29], v[4:5], v[46:47], v[28:29] op_sel_hi:[1,0,1]
	v_pk_fma_f32 v[4:5], v[90:91], v[50:51], v[4:5] op_sel_hi:[1,0,1]
	v_pk_fma_f32 v[28:29], v[6:7], v[46:47], v[28:29] op_sel:[0,1,0] op_sel_hi:[1,1,1]
	v_pk_fma_f32 v[6:7], v[90:91], v[50:51], v[6:7] op_sel:[0,1,0] op_sel_hi:[1,1,1]
	ds_read_b128 v[40:43], v134 offset:15872
	ds_read_b128 v[44:47], v134 offset:24064
	s_waitcnt lgkmcnt(7)
	v_pk_mul_f32 v[30:31], v[0:1], v[52:53] op_sel_hi:[1,0]
	v_pk_fma_f32 v[0:1], v[80:81], v[56:57], v[0:1] op_sel_hi:[1,0,1]
	v_pk_fma_f32 v[30:31], v[2:3], v[52:53], v[30:31] op_sel:[0,1,0] op_sel_hi:[1,1,1]
	v_pk_fma_f32 v[2:3], v[80:81], v[56:57], v[2:3] op_sel:[0,1,0] op_sel_hi:[1,1,1]
	v_pk_fma_f32 v[30:31], v[4:5], v[54:55], v[30:31] op_sel_hi:[1,0,1]
	v_pk_fma_f32 v[4:5], v[80:81], v[58:59], v[4:5] op_sel_hi:[1,0,1]
	v_pk_fma_f32 v[30:31], v[6:7], v[54:55], v[30:31] op_sel:[0,1,0] op_sel_hi:[1,1,1]
	v_pk_fma_f32 v[6:7], v[80:81], v[58:59], v[6:7] op_sel:[0,1,0] op_sel_hi:[1,1,1]
	s_waitcnt lgkmcnt(5)
	v_pk_mul_f32 v[32:33], v[0:1], v[60:61] op_sel_hi:[1,0]
	v_pk_fma_f32 v[0:1], v[82:83], v[64:65], v[0:1] op_sel_hi:[1,0,1]
	v_pk_fma_f32 v[32:33], v[2:3], v[60:61], v[32:33] op_sel:[0,1,0] op_sel_hi:[1,1,1]
	v_pk_fma_f32 v[2:3], v[82:83], v[64:65], v[2:3] op_sel:[0,1,0] op_sel_hi:[1,1,1]
	v_pk_fma_f32 v[32:33], v[4:5], v[62:63], v[32:33] op_sel_hi:[1,0,1]
	v_pk_fma_f32 v[4:5], v[82:83], v[66:67], v[4:5] op_sel_hi:[1,0,1]
	v_pk_fma_f32 v[32:33], v[6:7], v[62:63], v[32:33] op_sel:[0,1,0] op_sel_hi:[1,1,1]
	v_pk_fma_f32 v[6:7], v[82:83], v[66:67], v[6:7] op_sel:[0,1,0] op_sel_hi:[1,1,1]
	s_waitcnt lgkmcnt(2)
	v_pk_mul_f32 v[34:35], v[0:1], v[68:69] op_sel_hi:[1,0]
	v_pk_fma_f32 v[0:1], v[84:85], v[72:73], v[0:1] op_sel_hi:[1,0,1]
	v_pk_fma_f32 v[34:35], v[2:3], v[68:69], v[34:35] op_sel:[0,1,0] op_sel_hi:[1,1,1]
	v_pk_fma_f32 v[2:3], v[84:85], v[72:73], v[2:3] op_sel:[0,1,0] op_sel_hi:[1,1,1]
	v_pk_fma_f32 v[34:35], v[4:5], v[70:71], v[34:35] op_sel_hi:[1,0,1]
	v_pk_fma_f32 v[4:5], v[84:85], v[74:75], v[4:5] op_sel_hi:[1,0,1]
	v_pk_fma_f32 v[34:35], v[6:7], v[70:71], v[34:35] op_sel:[0,1,0] op_sel_hi:[1,1,1]
	v_pk_fma_f32 v[6:7], v[84:85], v[74:75], v[6:7] op_sel:[0,1,0] op_sel_hi:[1,1,1]
	s_waitcnt lgkmcnt(0)
	v_pk_mul_f32 v[36:37], v[0:1], v[76:77] op_sel_hi:[1,0]
	v_pk_fma_f32 v[0:1], v[86:87], v[40:41], v[0:1] op_sel_hi:[1,0,1]
	v_pk_fma_f32 v[36:37], v[2:3], v[76:77], v[36:37] op_sel:[0,1,0] op_sel_hi:[1,1,1]
	v_pk_fma_f32 v[2:3], v[86:87], v[40:41], v[2:3] op_sel:[0,1,0] op_sel_hi:[1,1,1]
	v_pk_fma_f32 v[36:37], v[4:5], v[78:79], v[36:37] op_sel_hi:[1,0,1]
	v_pk_fma_f32 v[4:5], v[86:87], v[42:43], v[4:5] op_sel_hi:[1,0,1]
	v_pk_fma_f32 v[36:37], v[6:7], v[78:79], v[36:37] op_sel:[0,1,0] op_sel_hi:[1,1,1]
	v_pk_fma_f32 v[6:7], v[86:87], v[42:43], v[6:7] op_sel:[0,1,0] op_sel_hi:[1,1,1]
	v_pk_mul_f32 v[38:39], v[0:1], v[44:45] op_sel_hi:[1,0]
	v_pk_fma_f32 v[38:39], v[2:3], v[44:45], v[38:39] op_sel:[0,1,0] op_sel_hi:[1,1,1]
	v_pk_fma_f32 v[38:39], v[4:5], v[46:47], v[38:39] op_sel_hi:[1,0,1]
	v_pk_fma_f32 v[38:39], v[6:7], v[46:47], v[38:39] op_sel:[0,1,0] op_sel_hi:[1,1,1]
	v_pk_mul_f32 v[0:1], v[0:1], v[192:193]
	v_pk_mul_f32 v[2:3], v[2:3], v[192:193]
	v_pk_mul_f32 v[4:5], v[4:5], v[192:193]
	v_pk_mul_f32 v[6:7], v[6:7], v[192:193]
	s_nop 1
	v_permlane16_swap_b32_e32 v8, v24
	v_permlane16_swap_b32_e32 v9, v25
	v_permlane16_swap_b32_e32 v10, v26
	v_permlane16_swap_b32_e32 v11, v27
	v_permlane16_swap_b32_e32 v12, v28
	v_permlane16_swap_b32_e32 v13, v29
	v_permlane16_swap_b32_e32 v14, v30
	v_permlane16_swap_b32_e32 v15, v31
	v_permlane16_swap_b32_e32 v16, v32
	v_permlane16_swap_b32_e32 v17, v33
	v_permlane16_swap_b32_e32 v18, v34
	v_permlane16_swap_b32_e32 v19, v35
	v_permlane16_swap_b32_e32 v20, v36
	v_permlane16_swap_b32_e32 v21, v37
	v_permlane16_swap_b32_e32 v22, v38
	v_permlane16_swap_b32_e32 v23, v39
	v_pk_add_f32 v[8:9], v[8:9], v[24:25]
	v_pk_add_f32 v[10:11], v[10:11], v[26:27]
	v_pk_add_f32 v[12:13], v[12:13], v[28:29]
	v_pk_add_f32 v[14:15], v[14:15], v[30:31]
	v_pk_add_f32 v[16:17], v[16:17], v[32:33]
	v_pk_add_f32 v[18:19], v[18:19], v[34:35]
	v_pk_add_f32 v[20:21], v[20:21], v[36:37]
	v_pk_add_f32 v[22:23], v[22:23], v[38:39]
	s_nop 1
	v_permlane32_swap_b32_e32 v8, v16
	v_permlane32_swap_b32_e32 v9, v17
	v_permlane32_swap_b32_e32 v10, v18
	v_permlane32_swap_b32_e32 v11, v19
	v_permlane32_swap_b32_e32 v12, v20
	v_permlane32_swap_b32_e32 v13, v21
	v_permlane32_swap_b32_e32 v14, v22
	v_permlane32_swap_b32_e32 v15, v23
	v_pk_add_f32 v[8:9], v[8:9], v[16:17]
	v_pk_add_f32 v[10:11], v[10:11], v[18:19]
	v_pk_add_f32 v[12:13], v[12:13], v[20:21]
	v_pk_add_f32 v[14:15], v[14:15], v[22:23]
	ds_write2_b32 v141, v8, v9 offset1:16
	ds_write2_b32 v142, v10, v11 offset1:16
	ds_write2_b32 v143, v12, v13 offset1:16
	ds_write2_b32 v144, v14, v15 offset1:16
	s_sub_u32 s15, s15, 1
	s_waitcnt lgkmcnt(0)
	s_barrier
	ds_read2_b32 v[104:105], v149 offset0:0 offset1:32
	ds_read2_b32 v[106:107], v149 offset0:64 offset1:96
	ds_read2_b32 v[108:109], v149 offset0:128 offset1:160
	ds_read2_b32 v[110:111], v149 offset0:192 offset1:224
	s_waitcnt vmcnt(7)
	v_lshlrev_b32_e32 v180, 16, v122
	v_and_b32_e32 v181, s69, v122
	v_lshlrev_b32_e32 v182, 16, v123
	v_and_b32_e32 v183, s69, v123
	s_cmp_eq_u32 s14, 0
	s_cbranch_scc1 .Lgla_st_join_5
	v_mul_f32_e32 v180, 0x3fb8aa3b, v180
	v_mul_f32_e32 v181, 0x3fb8aa3b, v181
	v_mul_f32_e32 v182, 0x3fb8aa3b, v182
	v_mul_f32_e32 v183, 0x3fb8aa3b, v183
	v_exp_f32_e32 v180, v180
	v_exp_f32_e32 v181, v181
	v_exp_f32_e32 v182, v182
	v_exp_f32_e32 v183, v183

.Lgla_st_nosc_5:
	ds_write_b128 v139, v[180:183] offset:8192
	ds_write_b128 v139, v[184:187] offset:16384
	ds_write2_b32 v140, v188, v189 offset1:4
	global_load_dwordx2 v[120:121], v130, s[8:9]
	global_load_dwordx2 v[122:123], v130, s[8:9] offset:1024
	global_load_dword v124, v131, s[8:9]
	s_add_u32 s8, s8, 0x34000
	s_addc_u32 s9, s9, 0
	s_waitcnt lgkmcnt(3)
	v_add_f32_e32 v112, v104, v105
	v_add_f32_e32 v112, v112, v106
	v_add_f32_e32 v112, v112, v107
	v_add_f32_e32 v112, v112, v108
	v_add_f32_e32 v112, v112, v109
	v_add_f32_e32 v112, v112, v110
	v_add_f32_e32 v112, v112, v111
	v_mul_f32_e32 v113, v112, v112
	v_cvt_pk_bf16_f32 v116, v112, v129
	v_mov_b32_e32 v117, v112
	v_mov_b32_e32 v118, v113
	global_store_short v132, v116, s[10:11]
	s_nop 1
	v_permlane16_swap_b32_e32 v112, v117
	v_permlane16_swap_b32_e32 v113, v118
	v_add_f32_e32 v112, v112, v117
	v_add_f32_e32 v113, v113, v118
	s_nop 1
	v_add_f32_dpp v112, v112, v112 row_ror:8 row_mask:0xf bank_mask:0xf
	v_add_f32_dpp v113, v113, v113 row_ror:8 row_mask:0xf bank_mask:0xf
	s_nop 1
	v_add_f32_dpp v112, v112, v112 row_ror:4 row_mask:0xf bank_mask:0xf
	v_add_f32_dpp v113, v113, v113 row_ror:4 row_mask:0xf bank_mask:0xf
	s_nop 1
	v_add_f32_dpp v112, v112, v112 row_ror:2 row_mask:0xf bank_mask:0xf
	v_add_f32_dpp v113, v113, v113 row_ror:2 row_mask:0xf bank_mask:0xf
	s_nop 1
	v_add_f32_dpp v112, v112, v112 row_ror:1 row_mask:0xf bank_mask:0xf
	v_add_f32_dpp v113, v113, v113 row_ror:1 row_mask:0xf bank_mask:0xf
	v_mov_b32_e32 v114, 0
	v_mov_b32_e32 v115, 0
	s_mov_b64 exec, s[18:19]
	global_store_dwordx4 v133, v[112:115], s[12:13]
	s_mov_b64 exec, -1
	s_cmp_eq_u32 s15, 512
	s_cselect_b32 s20, 0, 0x10000
	s_cselect_b32 s21, 0, 0x1000
	s_add_u32 s10, s10, s20
	s_addc_u32 s11, s11, 0
	s_add_u32 s12, s12, s21
	s_addc_u32 s13, s13, 0
	ds_read_b128 v[80:83], v135 offset:57344
	ds_read_b128 v[40:43], v134 offset:40960
	ds_read_b128 v[44:47], v134 offset:49152
	ds_read_b128 v[48:51], v134 offset:41472
	ds_read_b128 v[52:55], v134 offset:49664
	ds_read_b128 v[84:87], v135 offset:57600
	ds_read_b128 v[56:59], v134 offset:41984
	ds_read_b128 v[60:63], v134 offset:50176
	ds_read_b128 v[64:67], v134 offset:42496
	ds_read_b128 v[68:71], v134 offset:50688
	s_waitcnt lgkmcnt(7)
	v_pk_fma_f32 v[0:1], v[80:81], v[40:41], v[0:1] op_sel_hi:[1,0,1]
	v_pk_fma_f32 v[2:3], v[80:81], v[40:41], v[2:3] op_sel:[0,1,0] op_sel_hi:[1,1,1]
	v_pk_fma_f32 v[4:5], v[80:81], v[42:43], v[4:5] op_sel_hi:[1,0,1]
	v_pk_fma_f32 v[6:7], v[80:81], v[42:43], v[6:7] op_sel:[0,1,0] op_sel_hi:[1,1,1]
	ds_read_b128 v[88:91], v135 offset:57856
	ds_read_b128 v[72:75], v134 offset:43008
	ds_read_b128 v[76:79], v134 offset:51200
	s_waitcnt lgkmcnt(8)
	v_pk_mul_f32 v[8:9], v[0:1], v[44:45] op_sel_hi:[1,0]
	v_pk_fma_f32 v[0:1], v[82:83], v[48:49], v[0:1] op_sel_hi:[1,0,1]
	v_pk_fma_f32 v[8:9], v[2:3], v[44:45], v[8:9] op_sel:[0,1,0] op_sel_hi:[1,1,1]
	v_pk_fma_f32 v[2:3], v[82:83], v[48:49], v[2:3] op_sel:[0,1,0] op_sel_hi:[1,1,1]
	v_pk_fma_f32 v[8:9], v[4:5], v[46:47], v[8:9] op_sel_hi:[1,0,1]
	v_pk_fma_f32 v[4:5], v[82:83], v[50:51], v[4:5] op_sel_hi:[1,0,1]
	v_pk_fma_f32 v[8:9], v[6:7], v[46:47], v[8:9] op_sel:[0,1,0] op_sel_hi:[1,1,1]
	v_pk_fma_f32 v[6:7], v[82:83], v[50:51], v[6:7] op_sel:[0,1,0] op_sel_hi:[1,1,1]
	ds_read_b128 v[40:43], v134 offset:43520
	ds_read_b128 v[44:47], v134 offset:51712
	s_waitcnt lgkmcnt(7)
	v_pk_mul_f32 v[10:11], v[0:1], v[52:53] op_sel_hi:[1,0]
	v_pk_fma_f32 v[0:1], v[84:85], v[56:57], v[0:1] op_sel_hi:[1,0,1]
	v_pk_fma_f32 v[10:11], v[2:3], v[52:53], v[10:11] op_sel:[0,1,0] op_sel_hi:[1,1,1]
	v_pk_fma_f32 v[2:3], v[84:85], v[56:57], v[2:3] op_sel:[0,1,0] op_sel_hi:[1,1,1]
	v_pk_fma_f32 v[10:11], v[4:5], v[54:55], v[10:11] op_sel_hi:[1,0,1]
	v_pk_fma_f32 v[4:5], v[84:85], v[58:59], v[4:5] op_sel_hi:[1,0,1]
	v_pk_fma_f32 v[10:11], v[6:7], v[54:55], v[10:11] op_sel:[0,1,0] op_sel_hi:[1,1,1]
	v_pk_fma_f32 v[6:7], v[84:85], v[58:59], v[6:7] op_sel:[0,1,0] op_sel_hi:[1,1,1]
	ds_read_b128 v[80:83], v135 offset:58112
	ds_read_b128 v[48:51], v134 offset:44032
	ds_read_b128 v[52:55], v134 offset:52224
	s_waitcnt lgkmcnt(8)
	v_pk_mul_f32 v[12:13], v[0:1], v[60:61] op_sel_hi:[1,0]
	v_pk_fma_f32 v[0:1], v[86:87], v[64:65], v[0:1] op_sel_hi:[1,0,1]
	v_pk_fma_f32 v[12:13], v[2:3], v[60:61], v[12:13] op_sel:[0,1,0] op_sel_hi:[1,1,1]
	v_pk_fma_f32 v[2:3], v[86:87], v[64:65], v[2:3] op_sel:[0,1,0] op_sel_hi:[1,1,1]
	v_pk_fma_f32 v[12:13], v[4:5], v[62:63], v[12:13] op_sel_hi:[1,0,1]
	v_pk_fma_f32 v[4:5], v[86:87], v[66:67], v[4:5] op_sel_hi:[1,0,1]
	v_pk_fma_f32 v[12:13], v[6:7], v[62:63], v[12:13] op_sel:[0,1,0] op_sel_hi:[1,1,1]
	v_pk_fma_f32 v[6:7], v[86:87], v[66:67], v[6:7] op_sel:[0,1,0] op_sel_hi:[1,1,1]
	ds_read_b128 v[56:59], v134 offset:44544
	ds_read_b128 v[60:63], v134 offset:52736
	s_waitcnt lgkmcnt(7)
	v_pk_mul_f32 v[14:15], v[0:1], v[68:69] op_sel_hi:[1,0]
	v_pk_fma_f32 v[0:1], v[88:89], v[72:73], v[0:1] op_sel_hi:[1,0,1]
	v_pk_fma_f32 v[14:15], v[2:3], v[68:69], v[14:15] op_sel:[0,1,0] op_sel_hi:[1,1,1]
	v_pk_fma_f32 v[2:3], v[88:89], v[72:73], v[2:3] op_sel:[0,1,0] op_sel_hi:[1,1,1]
	v_pk_fma_f32 v[14:15], v[4:5], v[70:71], v[14:15] op_sel_hi:[1,0,1]
	v_pk_fma_f32 v[4:5], v[88:89], v[74:75], v[4:5] op_sel_hi:[1,0,1]
	v_pk_fma_f32 v[14:15], v[6:7], v[70:71], v[14:15] op_sel:[0,1,0] op_sel_hi:[1,1,1]
	v_pk_fma_f32 v[6:7], v[88:89], v[74:75], v[6:7] op_sel:[0,1,0] op_sel_hi:[1,1,1]
	ds_read_b128 v[84:87], v135 offset:58368
	ds_read_b128 v[64:67], v134 offset:45056
	ds_read_b128 v[68:71], v134 offset:53248
	s_waitcnt lgkmcnt(8)
	v_pk_mul_f32 v[16:17], v[0:1], v[76:77] op_sel_hi:[1,0]
	v_pk_fma_f32 v[0:1], v[90:91], v[40:41], v[0:1] op_sel_hi:[1,0,1]
	v_pk_fma_f32 v[16:17], v[2:3], v[76:77], v[16:17] op_sel:[0,1,0] op_sel_hi:[1,1,1]
	v_pk_fma_f32 v[2:3], v[90:91], v[40:41], v[2:3] op_sel:[0,1,0] op_sel_hi:[1,1,1]
	v_pk_fma_f32 v[16:17], v[4:5], v[78:79], v[16:17] op_sel_hi:[1,0,1]
	v_pk_fma_f32 v[4:5], v[90:91], v[42:43], v[4:5] op_sel_hi:[1,0,1]
	v_pk_fma_f32 v[16:17], v[6:7], v[78:79], v[16:17] op_sel:[0,1,0] op_sel_hi:[1,1,1]
	v_pk_fma_f32 v[6:7], v[90:91], v[42:43], v[6:7] op_sel:[0,1,0] op_sel_hi:[1,1,1]
	ds_read_b128 v[72:75], v134 offset:45568
	ds_read_b128 v[76:79], v134 offset:53760
	s_waitcnt lgkmcnt(7)
	v_pk_mul_f32 v[18:19], v[0:1], v[44:45] op_sel_hi:[1,0]
	v_pk_fma_f32 v[0:1], v[80:81], v[48:49], v[0:1] op_sel_hi:[1,0,1]
	v_pk_fma_f32 v[18:19], v[2:3], v[44:45], v[18:19] op_sel:[0,1,0] op_sel_hi:[1,1,1]
	v_pk_fma_f32 v[2:3], v[80:81], v[48:49], v[2:3] op_sel:[0,1,0] op_sel_hi:[1,1,1]
	v_pk_fma_f32 v[18:19], v[4:5], v[46:47], v[18:19] op_sel_hi:[1,0,1]
	v_pk_fma_f32 v[4:5], v[80:81], v[50:51], v[4:5] op_sel_hi:[1,0,1]
	v_pk_fma_f32 v[18:19], v[6:7], v[46:47], v[18:19] op_sel:[0,1,0] op_sel_hi:[1,1,1]
	v_pk_fma_f32 v[6:7], v[80:81], v[50:51], v[6:7] op_sel:[0,1,0] op_sel_hi:[1,1,1]
	ds_read_b128 v[88:91], v135 offset:58624
	ds_read_b128 v[40:43], v134 offset:46080
	ds_read_b128 v[44:47], v134 offset:54272
	s_waitcnt lgkmcnt(8)
	v_pk_mul_f32 v[20:21], v[0:1], v[52:53] op_sel_hi:[1,0]
	v_pk_fma_f32 v[0:1], v[82:83], v[56:57], v[0:1] op_sel_hi:[1,0,1]
	v_pk_fma_f32 v[20:21], v[2:3], v[52:53], v[20:21] op_sel:[0,1,0] op_sel_hi:[1,1,1]
	v_pk_fma_f32 v[2:3], v[82:83], v[56:57], v[2:3] op_sel:[0,1,0] op_sel_hi:[1,1,1]
	v_pk_fma_f32 v[20:21], v[4:5], v[54:55], v[20:21] op_sel_hi:[1,0,1]
	v_pk_fma_f32 v[4:5], v[82:83], v[58:59], v[4:5] op_sel_hi:[1,0,1]
	v_pk_fma_f32 v[20:21], v[6:7], v[54:55], v[20:21] op_sel:[0,1,0] op_sel_hi:[1,1,1]
	v_pk_fma_f32 v[6:7], v[82:83], v[58:59], v[6:7] op_sel:[0,1,0] op_sel_hi:[1,1,1]
	ds_read_b128 v[48:51], v134 offset:46592
	ds_read_b128 v[52:55], v134 offset:54784
	s_waitcnt lgkmcnt(7)
	v_pk_mul_f32 v[22:23], v[0:1], v[60:61] op_sel_hi:[1,0]
	v_pk_fma_f32 v[0:1], v[84:85], v[64:65], v[0:1] op_sel_hi:[1,0,1]
	v_pk_fma_f32 v[22:23], v[2:3], v[60:61], v[22:23] op_sel:[0,1,0] op_sel_hi:[1,1,1]
	v_pk_fma_f32 v[2:3], v[84:85], v[64:65], v[2:3] op_sel:[0,1,0] op_sel_hi:[1,1,1]
	v_pk_fma_f32 v[22:23], v[4:5], v[62:63], v[22:23] op_sel_hi:[1,0,1]
	v_pk_fma_f32 v[4:5], v[84:85], v[66:67], v[4:5] op_sel_hi:[1,0,1]
	v_pk_fma_f32 v[22:23], v[6:7], v[62:63], v[22:23] op_sel:[0,1,0] op_sel_hi:[1,1,1]
	v_pk_fma_f32 v[6:7], v[84:85], v[66:67], v[6:7] op_sel:[0,1,0] op_sel_hi:[1,1,1]
	ds_read_b128 v[80:83], v135 offset:58880
	ds_read_b128 v[56:59], v134 offset:47104
	ds_read_b128 v[60:63], v134 offset:55296
	s_waitcnt lgkmcnt(8)
	v_pk_mul_f32 v[24:25], v[0:1], v[68:69] op_sel_hi:[1,0]
	v_pk_fma_f32 v[0:1], v[86:87], v[72:73], v[0:1] op_sel_hi:[1,0,1]
	v_pk_fma_f32 v[24:25], v[2:3], v[68:69], v[24:25] op_sel:[0,1,0] op_sel_hi:[1,1,1]
	v_pk_fma_f32 v[2:3], v[86:87], v[72:73], v[2:3] op_sel:[0,1,0] op_sel_hi:[1,1,1]
	v_pk_fma_f32 v[24:25], v[4:5], v[70:71], v[24:25] op_sel_hi:[1,0,1]
	v_pk_fma_f32 v[4:5], v[86:87], v[74:75], v[4:5] op_sel_hi:[1,0,1]
	v_pk_fma_f32 v[24:25], v[6:7], v[70:71], v[24:25] op_sel:[0,1,0] op_sel_hi:[1,1,1]
	v_pk_fma_f32 v[6:7], v[86:87], v[74:75], v[6:7] op_sel:[0,1,0] op_sel_hi:[1,1,1]
	ds_read_b128 v[64:67], v134 offset:47616
	ds_read_b128 v[68:71], v134 offset:55808
	s_waitcnt lgkmcnt(7)
	v_pk_mul_f32 v[26:27], v[0:1], v[76:77] op_sel_hi:[1,0]
	v_pk_fma_f32 v[0:1], v[88:89], v[40:41], v[0:1] op_sel_hi:[1,0,1]
	v_pk_fma_f32 v[26:27], v[2:3], v[76:77], v[26:27] op_sel:[0,1,0] op_sel_hi:[1,1,1]
	v_pk_fma_f32 v[2:3], v[88:89], v[40:41], v[2:3] op_sel:[0,1,0] op_sel_hi:[1,1,1]
	v_pk_fma_f32 v[26:27], v[4:5], v[78:79], v[26:27] op_sel_hi:[1,0,1]
	v_pk_fma_f32 v[4:5], v[88:89], v[42:43], v[4:5] op_sel_hi:[1,0,1]
	v_pk_fma_f32 v[26:27], v[6:7], v[78:79], v[26:27] op_sel:[0,1,0] op_sel_hi:[1,1,1]
	v_pk_fma_f32 v[6:7], v[88:89], v[42:43], v[6:7] op_sel:[0,1,0] op_sel_hi:[1,1,1]
	ds_read_b128 v[84:87], v135 offset:59136
	ds_read_b128 v[72:75], v134 offset:48128
	ds_read_b128 v[76:79], v134 offset:56320
	s_waitcnt lgkmcnt(8)
	v_pk_mul_f32 v[28:29], v[0:1], v[44:45] op_sel_hi:[1,0]
	v_pk_fma_f32 v[0:1], v[90:91], v[48:49], v[0:1] op_sel_hi:[1,0,1]
	v_pk_fma_f32 v[28:29], v[2:3], v[44:45], v[28:29] op_sel:[0,1,0] op_sel_hi:[1,1,1]
	v_pk_fma_f32 v[2:3], v[90:91], v[48:49], v[2:3] op_sel:[0,1,0] op_sel_hi:[1,1,1]
	v_pk_fma_f32 v[28:29], v[4:5], v[46:47], v[28:29] op_sel_hi:[1,0,1]
	v_pk_fma_f32 v[4:5], v[90:91], v[50:51], v[4:5] op_sel_hi:[1,0,1]
	v_pk_fma_f32 v[28:29], v[6:7], v[46:47], v[28:29] op_sel:[0,1,0] op_sel_hi:[1,1,1]
	v_pk_fma_f32 v[6:7], v[90:91], v[50:51], v[6:7] op_sel:[0,1,0] op_sel_hi:[1,1,1]
	ds_read_b128 v[40:43], v134 offset:48640
	ds_read_b128 v[44:47], v134 offset:56832
	s_waitcnt lgkmcnt(7)
	v_pk_mul_f32 v[30:31], v[0:1], v[52:53] op_sel_hi:[1,0]
	v_pk_fma_f32 v[0:1], v[80:81], v[56:57], v[0:1] op_sel_hi:[1,0,1]
	v_pk_fma_f32 v[30:31], v[2:3], v[52:53], v[30:31] op_sel:[0,1,0] op_sel_hi:[1,1,1]
	v_pk_fma_f32 v[2:3], v[80:81], v[56:57], v[2:3] op_sel:[0,1,0] op_sel_hi:[1,1,1]
	v_pk_fma_f32 v[30:31], v[4:5], v[54:55], v[30:31] op_sel_hi:[1,0,1]
	v_pk_fma_f32 v[4:5], v[80:81], v[58:59], v[4:5] op_sel_hi:[1,0,1]
	v_pk_fma_f32 v[30:31], v[6:7], v[54:55], v[30:31] op_sel:[0,1,0] op_sel_hi:[1,1,1]
	v_pk_fma_f32 v[6:7], v[80:81], v[58:59], v[6:7] op_sel:[0,1,0] op_sel_hi:[1,1,1]
	s_waitcnt lgkmcnt(5)
	v_pk_mul_f32 v[32:33], v[0:1], v[60:61] op_sel_hi:[1,0]
	v_pk_fma_f32 v[0:1], v[82:83], v[64:65], v[0:1] op_sel_hi:[1,0,1]
	v_pk_fma_f32 v[32:33], v[2:3], v[60:61], v[32:33] op_sel:[0,1,0] op_sel_hi:[1,1,1]
	v_pk_fma_f32 v[2:3], v[82:83], v[64:65], v[2:3] op_sel:[0,1,0] op_sel_hi:[1,1,1]
	v_pk_fma_f32 v[32:33], v[4:5], v[62:63], v[32:33] op_sel_hi:[1,0,1]
	v_pk_fma_f32 v[4:5], v[82:83], v[66:67], v[4:5] op_sel_hi:[1,0,1]
	v_pk_fma_f32 v[32:33], v[6:7], v[62:63], v[32:33] op_sel:[0,1,0] op_sel_hi:[1,1,1]
	v_pk_fma_f32 v[6:7], v[82:83], v[66:67], v[6:7] op_sel:[0,1,0] op_sel_hi:[1,1,1]
	s_waitcnt lgkmcnt(2)
	v_pk_mul_f32 v[34:35], v[0:1], v[68:69] op_sel_hi:[1,0]
	v_pk_fma_f32 v[0:1], v[84:85], v[72:73], v[0:1] op_sel_hi:[1,0,1]
	v_pk_fma_f32 v[34:35], v[2:3], v[68:69], v[34:35] op_sel:[0,1,0] op_sel_hi:[1,1,1]
	v_pk_fma_f32 v[2:3], v[84:85], v[72:73], v[2:3] op_sel:[0,1,0] op_sel_hi:[1,1,1]
	v_pk_fma_f32 v[34:35], v[4:5], v[70:71], v[34:35] op_sel_hi:[1,0,1]
	v_pk_fma_f32 v[4:5], v[84:85], v[74:75], v[4:5] op_sel_hi:[1,0,1]
	v_pk_fma_f32 v[34:35], v[6:7], v[70:71], v[34:35] op_sel:[0,1,0] op_sel_hi:[1,1,1]
	v_pk_fma_f32 v[6:7], v[84:85], v[74:75], v[6:7] op_sel:[0,1,0] op_sel_hi:[1,1,1]
	s_waitcnt lgkmcnt(0)
	v_pk_mul_f32 v[36:37], v[0:1], v[76:77] op_sel_hi:[1,0]
	v_pk_fma_f32 v[0:1], v[86:87], v[40:41], v[0:1] op_sel_hi:[1,0,1]
	v_pk_fma_f32 v[36:37], v[2:3], v[76:77], v[36:37] op_sel:[0,1,0] op_sel_hi:[1,1,1]
	v_pk_fma_f32 v[2:3], v[86:87], v[40:41], v[2:3] op_sel:[0,1,0] op_sel_hi:[1,1,1]
	v_pk_fma_f32 v[36:37], v[4:5], v[78:79], v[36:37] op_sel_hi:[1,0,1]
	v_pk_fma_f32 v[4:5], v[86:87], v[42:43], v[4:5] op_sel_hi:[1,0,1]
	v_pk_fma_f32 v[36:37], v[6:7], v[78:79], v[36:37] op_sel:[0,1,0] op_sel_hi:[1,1,1]
	v_pk_fma_f32 v[6:7], v[86:87], v[42:43], v[6:7] op_sel:[0,1,0] op_sel_hi:[1,1,1]
	v_pk_mul_f32 v[38:39], v[0:1], v[44:45] op_sel_hi:[1,0]
	v_pk_fma_f32 v[38:39], v[2:3], v[44:45], v[38:39] op_sel:[0,1,0] op_sel_hi:[1,1,1]
	v_pk_fma_f32 v[38:39], v[4:5], v[46:47], v[38:39] op_sel_hi:[1,0,1]
	v_pk_fma_f32 v[38:39], v[6:7], v[46:47], v[38:39] op_sel:[0,1,0] op_sel_hi:[1,1,1]
	v_pk_mul_f32 v[0:1], v[0:1], v[192:193]
	v_pk_mul_f32 v[2:3], v[2:3], v[192:193]
	v_pk_mul_f32 v[4:5], v[4:5], v[192:193]
	v_pk_mul_f32 v[6:7], v[6:7], v[192:193]
	s_nop 1
	v_permlane16_swap_b32_e32 v8, v24
	v_permlane16_swap_b32_e32 v9, v25
	v_permlane16_swap_b32_e32 v10, v26
	v_permlane16_swap_b32_e32 v11, v27
	v_permlane16_swap_b32_e32 v12, v28
	v_permlane16_swap_b32_e32 v13, v29
	v_permlane16_swap_b32_e32 v14, v30
	v_permlane16_swap_b32_e32 v15, v31
	v_permlane16_swap_b32_e32 v16, v32
	v_permlane16_swap_b32_e32 v17, v33
	v_permlane16_swap_b32_e32 v18, v34
	v_permlane16_swap_b32_e32 v19, v35
	v_permlane16_swap_b32_e32 v20, v36
	v_permlane16_swap_b32_e32 v21, v37
	v_permlane16_swap_b32_e32 v22, v38
	v_permlane16_swap_b32_e32 v23, v39
	v_pk_add_f32 v[8:9], v[8:9], v[24:25]
	v_pk_add_f32 v[10:11], v[10:11], v[26:27]
	v_pk_add_f32 v[12:13], v[12:13], v[28:29]
	v_pk_add_f32 v[14:15], v[14:15], v[30:31]
	v_pk_add_f32 v[16:17], v[16:17], v[32:33]
	v_pk_add_f32 v[18:19], v[18:19], v[34:35]
	v_pk_add_f32 v[20:21], v[20:21], v[36:37]
	v_pk_add_f32 v[22:23], v[22:23], v[38:39]
	s_nop 1
	v_permlane32_swap_b32_e32 v8, v16
	v_permlane32_swap_b32_e32 v9, v17
	v_permlane32_swap_b32_e32 v10, v18
	v_permlane32_swap_b32_e32 v11, v19
	v_permlane32_swap_b32_e32 v12, v20
	v_permlane32_swap_b32_e32 v13, v21
	v_permlane32_swap_b32_e32 v14, v22
	v_permlane32_swap_b32_e32 v15, v23
	v_pk_add_f32 v[8:9], v[8:9], v[16:17]
	v_pk_add_f32 v[10:11], v[10:11], v[18:19]
	v_pk_add_f32 v[12:13], v[12:13], v[20:21]
	v_pk_add_f32 v[14:15], v[14:15], v[22:23]
	ds_write2_b32 v145, v8, v9 offset1:16
	ds_write2_b32 v146, v10, v11 offset1:16
	ds_write2_b32 v147, v12, v13 offset1:16
	ds_write2_b32 v148, v14, v15 offset1:16
	s_sub_u32 s15, s15, 1
	s_waitcnt lgkmcnt(0)
	s_barrier
	s_cmp_lg_u32 s15, 0
	s_cbranch_scc1 .Lgla_loop_ret
